# gate-column GEMM jobs: bias loaded once, no per-block waits; diff-attention column tiles of the input projection moved into the jobs phase (completion counter)
# baseline (speedup 1.0000x reference)
; __device__ __forceinline__ int tid_opaque() { int t; asm volatile("v_mov_b32 %0, %1" : "=v"(t) : "v"((int)threadIdx.x)); __builtin_assume(t >= 0 && t < NTHREADS); return t; }
;     __device__ __forceinline__ const void* in(int i) const { return (const void*)uni64(t[i]); }
; __device__ __forceinline__ void jobs_phase(LAS unsigned char* lds, const AP a, int l, int grp, int rep) {
;     ...
;         if (tid_opaque() == 0) *jslot = (int)__hip_atomic_fetch_add(ctr, 1u, __ATOMIC_RELAXED, __HIP_MEMORY_SCOPE_AGENT);
;         __syncthreads();
;         int j = *jslot;
;         __syncthreads();
;     ...
;         if (rep == 1) { if (JOBSEL == 1) { if (j >= NSCAN) break; } else j += NSCAN; }
;     ...
;         if (j >= NJOBS) break;
;         if (j < NSCAN) scan_job(lds, a, l, j >> 4, (j >> 1) & 7, j & 1);
;         else if (j >= NSCAN + NATT) {
;             const int gq = j - NSCAN - NATT, pn = 15 + 2 * (gq / (TG / 256)), pm = gq % (TG / 256);
;             Epi E; E.kind = K_P; E.aux = 0; E.grp = grp; E.pad = 0; E.ws = a.ws(); E.f0 = (const float*)a.in(I_BGATE) + l * GT_COLS; E.f1 = nullptr; E.xi = nullptr; E.xo = nullptr;
;             run_gemm_unit(lds, (const bf16_t*)(a.ws() + WS_HB), 1024, (const bf16_t*)(a.ws() + WT_IN), TG, NP, 1024, E, pm, pn, 2);
;             __syncthreads(); }
;         else { const int q = j - NSCAN, d = q / 96, r = q - d * 96;
;             if (r < 32) mla_unit(lds, a, r >> 3, r & 7, 7 - d);
;             else { const int rr = r - 32; diff_unit(lds, a, l, grp, (rr & 15) >> 2, rr & 3, 31 - 4 * d - (rr >> 4)); } }
.LBB0_125:
	s_or_b64 exec, exec, s[0:1]
	v_readlane_b32 s0, v254, 29
	s_waitcnt lgkmcnt(0)
	s_barrier
	v_mov_b32_e32 v0, s0
	ds_read_b32 v0, v0
	s_movk_i32 s0, 0x57f
	s_waitcnt lgkmcnt(0)
	s_barrier
	v_cmp_lt_i32_e32 vcc, s0, v0
	v_readfirstlane_b32 s23, v0
	s_mov_b64 s[0:1], -1
	s_cbranch_vccnz .LBB0_122
	s_cmp_gt_i32 s23, 63
	s_cbranch_scc0 .LBB0_236
	s_cmpk_lt_u32 s23, 0x100
	s_cbranch_scc1 .Lpd_entry
	s_sub_i32 s23, s23, 0xc0
	s_cmpk_lt_u32 s23, 0x340
	s_cbranch_scc0 .LBB0_225
	s_sub_i32 s0, s23, 64
	s_mul_i32 s1, s0, 0xaaab
	s_lshr_b32 s22, s1, 22
	s_mul_i32 s1, s22, 0xffffffa0
	s_add_i32 s16, s1, s0
	s_cmp_gt_i32 s16, 31
	s_mov_b64 s[0:1], -1
	s_cbranch_scc0 .LBB0_188
	v_mov_b64_e32 v[2:3], s[96:97]
	s_mov_b32 s99, 0
.Lpd_spin:
	flat_load_dword v0, v[2:3] offset:32 sc1
	s_waitcnt vmcnt(0) lgkmcnt(0)
	v_readfirstlane_b32 s98, v0
	s_cmpk_gt_u32 s98, 0xbf
	s_cbranch_scc1 .Lpd_seen
	s_sleep 8
	s_add_i32 s99, s99, 1
	s_cmpk_lt_u32 s99, 0x600
	s_cbranch_scc1 .Lpd_spin

; #define LAS __attribute__((address_space(3)))
; __device__ __forceinline__ int tid_opaque() { int t; asm volatile("v_mov_b32 %0, %1" : "=v"(t) : "v"((int)threadIdx.x)); __builtin_assume(t >= 0 && t < NTHREADS); return t; }
;     __device__ __forceinline__ const void* in(int i) const { return (const void*)uni64(t[i]); }
; __device__ __forceinline__ void diff_unit(LAS unsigned char* lds, const AP a, int l, int grp, int bl, int hd, int qb) {
;     const int tid = tid_opaque(), wave = tid >> 6, lane = tid & 63, n = lane & 31, g = lane >> 5, map = wave >> 2, qs = wave & 3;
;     constexpr int KSTR = 136, VSTR = 72, KB_BYTES = 64 * KSTR * 2, VB_BYTES = 128 * VSTR * 2, BUF = KB_BYTES + VB_BYTES;
;     constexpr int OFF_POS = 3 * BUF, OFF_LUT = OFF_POS + (3 * 64 + 4) * 4;
;     constexpr int XSTR = 132;
;     const bf16_t* QK = (const bf16_t*)(a.ws() + WS_QKD) + (size_t)bl * S * 1024;
;     const bf16_t* Vp = (const bf16_t*)(a.ws() + WS_VTD) + (size_t)(bl * 4 + hd) * 128 * S;
;     const int* pos = (const int*)a.in(I_POS) + (size_t)(grp * GB + bl) * S;
;     const int q0 = qb * 128 + qs * 32;
;     LAS float* lut = (LAS float*)(lds + OFF_LUT); LAS int* posk = (LAS int*)(lds + OFF_POS);
;     if (tid < 129) lut[tid] = ((const float*)a.in(I_RELB))[t5_bucket(tid) * 4 + hd] * LOG2E;
.Lpd_go:
	v_mov_b32_e32 v0, s73
	v_mov_b32 v182, v192
	s_waitcnt vmcnt(0)
	ds_read_b64 v[2:3], v0
	v_readlane_b32 s0, v254, 30
	s_and_b32 s15, s23, 3
	s_waitcnt lgkmcnt(0)
	v_readfirstlane_b32 s12, v3
	v_mov_b32_e32 v0, s0
	v_readfirstlane_b32 s17, v2
	ds_read_b64 v[2:3], v0
	s_movk_i32 s0, 0x81
	v_cmp_gt_u32_e32 vcc, s0, v182
	s_waitcnt lgkmcnt(0)
	v_readfirstlane_b32 s19, v3
	v_readfirstlane_b32 s20, v2
	s_and_saveexec_b64 s[0:1], vcc
	s_cbranch_execz .LBB0_133
	v_readlane_b32 s2, v254, 31
	v_cmp_lt_u32_e32 vcc, 15, v182
	s_nop 0
	v_mov_b32_e32 v0, s2
	ds_read_b64 v[2:3], v0
	v_mov_b32_e32 v0, v182
	s_waitcnt lgkmcnt(0)
	v_readfirstlane_b32 s3, v3
	v_readfirstlane_b32 s2, v2
	s_and_saveexec_b64 s[4:5], vcc
	s_cbranch_execz .LBB0_132
	v_cvt_f32_u32_e32 v0, v182
	s_mov_b32 s6, 0x3f317217
	s_mov_b32 s14, 0x40051592
	v_mul_f32_e32 v0, 0x3d800000, v0
	v_cmp_gt_f32_e32 vcc, s81, v0
	s_nop 1
	v_cndmask_b32_e64 v2, 0, 32, vcc
	v_ldexp_f32 v0, v0, v2
	v_log_f32_e32 v0, v0
	v_mov_b32_e32 v2, 0x41b17218
	v_cndmask_b32_e32 v2, 0, v2, vcc
	v_mul_f32_e32 v3, 0x3f317217, v0
	v_fma_f32 v3, v0, s6, -v3
	v_fmac_f32_e32 v3, 0x3377d1cf, v0
	v_fmac_f32_e32 v3, 0x3f317217, v0
	v_cmp_lt_f32_e64 vcc, |v0|, s82
	s_nop 1
	v_cndmask_b32_e32 v0, v0, v3, vcc
	v_sub_f32_e32 v0, v0, v2
	v_div_scale_f32 v2, s[6:7], s14, s14, v0
	v_rcp_f32_e32 v3, v2
	v_div_scale_f32 v4, vcc, v0, s14, v0
	v_fma_f32 v5, -v2, v3, 1.0
	v_fmac_f32_e32 v3, v5, v3
	v_mul_f32_e32 v5, v4, v3
	v_fma_f32 v6, -v2, v5, v4
	v_fmac_f32_e32 v5, v6, v3
	v_fma_f32 v2, -v2, v5, v4
	v_div_fmas_f32 v2, v2, v3, v5
	v_div_fixup_f32 v0, v2, s14, v0
	v_mul_f32_e32 v0, 0x41800000, v0
	v_cvt_i32_f32_e32 v0, v0
	v_min_i32_e32 v0, 15, v0
	v_add_u32_e32 v0, 16, v0

;     __device__ __forceinline__ void emit(int row, int pn, int col0, float* v) const {
;     ...
;             else if (pn < 13) { const int cq = col0 - 2304; if (cq < 512) {
; #pragma unroll
;                     for (int j = 0; j < 8; ++j) v[j] *= QSCALE_D; }
;                 store8((bf16_t*)(ws + WS_QKD) + (size_t)row * 1024 + cq, v); }
.Lpd_epi:
	v_lshl_or_b32 v163, s2, 8, v161
	s_and_b32 s22, s23, 63
	s_lshl_b32 s98, s22, 19
	s_sub_u32 s98, s45, s98
	s_subb_u32 s99, s46, 0
	v_and_b32_e32 v0, 15, v192
	s_lshl_b32 s22, s22, 8
	v_or_b32_e32 v0, s22, v0
	s_lshr_b32 s22, s27, 8
	s_lshl_b32 s22, s22, 6
	v_or_b32_e32 v0, s22, v0
	s_cmp_gt_i32 s2, 12
	s_cbranch_scc1 .Lpd_vtd
	s_add_u32 s98, s98, 0x9500000
	s_addc_u32 s99, s99, 0
	v_lshlrev_b32_e32 v0, 11, v0
	v_lshl_add_u32 v0, v163, 1, v0
	v_add_u32_e32 v0, 0xffffee00, v0
	s_cmp_gt_i32 s2, 10
	s_cbranch_scc1 .Lpd_qk_ns
	v_mul_f32_e32 v2, 0x3e38aa3b, v2
	v_mul_f32_e32 v3, 0x3e38aa3b, v3
	v_mul_f32_e32 v4, 0x3e38aa3b, v4
	v_mul_f32_e32 v5, 0x3e38aa3b, v5
	v_mul_f32_e32 v6, 0x3e38aa3b, v6
	v_mul_f32_e32 v7, 0x3e38aa3b, v7
	v_mul_f32_e32 v8, 0x3e38aa3b, v8
	v_mul_f32_e32 v9, 0x3e38aa3b, v9
	v_mul_f32_e32 v10, 0x3e38aa3b, v10
	v_mul_f32_e32 v11, 0x3e38aa3b, v11
	v_mul_f32_e32 v12, 0x3e38aa3b, v12
	v_mul_f32_e32 v13, 0x3e38aa3b, v13
	v_mul_f32_e32 v14, 0x3e38aa3b, v14
	v_mul_f32_e32 v15, 0x3e38aa3b, v15
	v_mul_f32_e32 v16, 0x3e38aa3b, v16
	v_mul_f32_e32 v17, 0x3e38aa3b, v17
	v_mul_f32_e32 v18, 0x3e38aa3b, v18
	v_mul_f32_e32 v19, 0x3e38aa3b, v19
	v_mul_f32_e32 v20, 0x3e38aa3b, v20
	v_mul_f32_e32 v21, 0x3e38aa3b, v21
	v_mul_f32_e32 v22, 0x3e38aa3b, v22
	v_mul_f32_e32 v23, 0x3e38aa3b, v23
	v_mul_f32_e32 v24, 0x3e38aa3b, v24
	v_mul_f32_e32 v25, 0x3e38aa3b, v25
	v_mul_f32_e32 v26, 0x3e38aa3b, v26
	v_mul_f32_e32 v27, 0x3e38aa3b, v27
	v_mul_f32_e32 v28, 0x3e38aa3b, v28
	v_mul_f32_e32 v29, 0x3e38aa3b, v29
	v_mul_f32_e32 v30, 0x3e38aa3b, v30
	v_mul_f32_e32 v31, 0x3e38aa3b, v31
	v_mul_f32_e32 v32, 0x3e38aa3b, v32
	v_mul_f32_e32 v33, 0x3e38aa3b, v33
	v_mul_f32_e32 v34, 0x3e38aa3b, v34
	v_mul_f32_e32 v35, 0x3e38aa3b, v35
	v_mul_f32_e32 v36, 0x3e38aa3b, v36
	v_mul_f32_e32 v37, 0x3e38aa3b, v37
	v_mul_f32_e32 v38, 0x3e38aa3b, v38
	v_mul_f32_e32 v39, 0x3e38aa3b, v39
	v_mul_f32_e32 v40, 0x3e38aa3b, v40
	v_mul_f32_e32 v41, 0x3e38aa3b, v41
	v_mul_f32_e32 v42, 0x3e38aa3b, v42
	v_mul_f32_e32 v43, 0x3e38aa3b, v43
	v_mul_f32_e32 v44, 0x3e38aa3b, v44
	v_mul_f32_e32 v45, 0x3e38aa3b, v45
	v_mul_f32_e32 v46, 0x3e38aa3b, v46
	v_mul_f32_e32 v47, 0x3e38aa3b, v47
	v_mul_f32_e32 v48, 0x3e38aa3b, v48
	v_mul_f32_e32 v49, 0x3e38aa3b, v49
	v_mul_f32_e32 v50, 0x3e38aa3b, v50
	v_mul_f32_e32 v51, 0x3e38aa3b, v51
	v_mul_f32_e32 v52, 0x3e38aa3b, v52
	v_mul_f32_e32 v53, 0x3e38aa3b, v53
	v_mul_f32_e32 v54, 0x3e38aa3b, v54
	v_mul_f32_e32 v55, 0x3e38aa3b, v55
	v_mul_f32_e32 v56, 0x3e38aa3b, v56
	v_mul_f32_e32 v57, 0x3e38aa3b, v57
	v_mul_f32_e32 v58, 0x3e38aa3b, v58
	v_mul_f32_e32 v59, 0x3e38aa3b, v59
	v_mul_f32_e32 v60, 0x3e38aa3b, v60
	v_mul_f32_e32 v61, 0x3e38aa3b, v61
	v_mul_f32_e32 v62, 0x3e38aa3b, v62
	v_mul_f32_e32 v63, 0x3e38aa3b, v63
	v_mul_f32_e32 v64, 0x3e38aa3b, v64
	v_mul_f32_e32 v65, 0x3e38aa3b, v65
	v_mul_f32_e32 v66, 0x3e38aa3b, v66
	v_mul_f32_e32 v67, 0x3e38aa3b, v67
	v_mul_f32_e32 v68, 0x3e38aa3b, v68
	v_mul_f32_e32 v69, 0x3e38aa3b, v69
	v_mul_f32_e32 v70, 0x3e38aa3b, v70
	v_mul_f32_e32 v71, 0x3e38aa3b, v71
	v_mul_f32_e32 v72, 0x3e38aa3b, v72
	v_mul_f32_e32 v73, 0x3e38aa3b, v73
	v_mul_f32_e32 v74, 0x3e38aa3b, v74
	v_mul_f32_e32 v75, 0x3e38aa3b, v75
	v_mul_f32_e32 v76, 0x3e38aa3b, v76
	v_mul_f32_e32 v77, 0x3e38aa3b, v77
	v_mul_f32_e32 v78, 0x3e38aa3b, v78
	v_mul_f32_e32 v79, 0x3e38aa3b, v79
	v_mul_f32_e32 v80, 0x3e38aa3b, v80
	v_mul_f32_e32 v81, 0x3e38aa3b, v81
	v_mul_f32_e32 v82, 0x3e38aa3b, v82
	v_mul_f32_e32 v83, 0x3e38aa3b, v83
	v_mul_f32_e32 v84, 0x3e38aa3b, v84
	v_mul_f32_e32 v85, 0x3e38aa3b, v85
	v_mul_f32_e32 v86, 0x3e38aa3b, v86
	v_mul_f32_e32 v87, 0x3e38aa3b, v87
	v_mul_f32_e32 v88, 0x3e38aa3b, v88
	v_mul_f32_e32 v89, 0x3e38aa3b, v89
	v_mul_f32_e32 v90, 0x3e38aa3b, v90
	v_mul_f32_e32 v91, 0x3e38aa3b, v91
	v_mul_f32_e32 v92, 0x3e38aa3b, v92
	v_mul_f32_e32 v93, 0x3e38aa3b, v93
	v_mul_f32_e32 v94, 0x3e38aa3b, v94
	v_mul_f32_e32 v95, 0x3e38aa3b, v95
	v_mul_f32_e32 v96, 0x3e38aa3b, v96
	v_mul_f32_e32 v97, 0x3e38aa3b, v97
	v_mul_f32_e32 v98, 0x3e38aa3b, v98
	v_mul_f32_e32 v99, 0x3e38aa3b, v99
	v_mul_f32_e32 v100, 0x3e38aa3b, v100
	v_mul_f32_e32 v101, 0x3e38aa3b, v101
	v_mul_f32_e32 v102, 0x3e38aa3b, v102
	v_mul_f32_e32 v103, 0x3e38aa3b, v103
	v_mul_f32_e32 v104, 0x3e38aa3b, v104
	v_mul_f32_e32 v105, 0x3e38aa3b, v105
	v_mul_f32_e32 v106, 0x3e38aa3b, v106
	v_mul_f32_e32 v107, 0x3e38aa3b, v107
	v_mul_f32_e32 v108, 0x3e38aa3b, v108
	v_mul_f32_e32 v109, 0x3e38aa3b, v109
	v_mul_f32_e32 v110, 0x3e38aa3b, v110
	v_mul_f32_e32 v111, 0x3e38aa3b, v111
	v_mul_f32_e32 v112, 0x3e38aa3b, v112
	v_mul_f32_e32 v113, 0x3e38aa3b, v113
	v_mul_f32_e32 v114, 0x3e38aa3b, v114
	v_mul_f32_e32 v115, 0x3e38aa3b, v115
	v_mul_f32_e32 v116, 0x3e38aa3b, v116
	v_mul_f32_e32 v117, 0x3e38aa3b, v117
	v_mul_f32_e32 v118, 0x3e38aa3b, v118
	v_mul_f32_e32 v119, 0x3e38aa3b, v119
	v_mul_f32_e32 v120, 0x3e38aa3b, v120
	v_mul_f32_e32 v121, 0x3e38aa3b, v121
	v_mul_f32_e32 v122, 0x3e38aa3b, v122
	v_mul_f32_e32 v123, 0x3e38aa3b, v123
	v_mul_f32_e32 v124, 0x3e38aa3b, v124
	v_mul_f32_e32 v125, 0x3e38aa3b, v125
	v_mul_f32_e32 v126, 0x3e38aa3b, v126
	v_mul_f32_e32 v127, 0x3e38aa3b, v127
	v_mul_f32_e32 v128, 0x3e38aa3b, v128
	v_mul_f32_e32 v129, 0x3e38aa3b, v129
; __device__ __forceinline__ bf16_t f2bf(float f) { return (bf16_t)(cvt_pk_bf16(f, 0.f) & 0xffffu); }
;     __device__ __forceinline__ void emit(int row, int pn, int col0, float* v) const {
;     ...
;                 store8((bf16_t*)(ws + WS_QKD) + (size_t)row * 1024 + cq, v); }
;             else if (pn < 15) { const int cv = col0 - 3328, hh = cv >> 7, dv = cv & 127, bl = row >> 12, s = row & 4095;
;                 bf16_t* p = (bf16_t*)(ws + WS_VTD) + ((size_t)(bl * 4 + hh) * 128 + dv) * S + s;
; #pragma unroll
;                 for (int j = 0; j < 8; ++j) p[(size_t)j * S] = f2bf(v[j]); }
.Lpd_qk_ns:
	v_cvt_pk_bf16_f32 v126, v126, v127
	v_cvt_pk_bf16_f32 v127, v128, v129
	v_cvt_pk_bf16_f32 v128, v122, v123
	v_cvt_pk_bf16_f32 v129, v124, v125
	global_store_dwordx4 v0, v[126:129], s[98:99]
	v_cvt_pk_bf16_f32 v118, v118, v119
	v_cvt_pk_bf16_f32 v119, v120, v121
	v_cvt_pk_bf16_f32 v120, v114, v115
	v_cvt_pk_bf16_f32 v121, v116, v117
	v_add_u32_e32 v158, 0x100, v0
	global_store_dwordx4 v158, v[118:121], s[98:99]
	v_cvt_pk_bf16_f32 v110, v110, v111
	v_cvt_pk_bf16_f32 v111, v112, v113
	v_cvt_pk_bf16_f32 v112, v106, v107
	v_cvt_pk_bf16_f32 v113, v108, v109
	v_add_u32_e32 v159, 0x8000, v0
	global_store_dwordx4 v159, v[110:113], s[98:99]
	v_cvt_pk_bf16_f32 v102, v102, v103
	v_cvt_pk_bf16_f32 v103, v104, v105
	v_cvt_pk_bf16_f32 v104, v98, v99
	v_cvt_pk_bf16_f32 v105, v100, v101
	v_add_u32_e32 v164, 0x8100, v0
	global_store_dwordx4 v164, v[102:105], s[98:99]
	v_cvt_pk_bf16_f32 v94, v94, v95
	v_cvt_pk_bf16_f32 v95, v96, v97
	v_cvt_pk_bf16_f32 v96, v90, v91
	v_cvt_pk_bf16_f32 v97, v92, v93
	v_add_u32_e32 v165, 0x10000, v0
	global_store_dwordx4 v165, v[94:97], s[98:99]
	v_cvt_pk_bf16_f32 v86, v86, v87
	v_cvt_pk_bf16_f32 v87, v88, v89
	v_cvt_pk_bf16_f32 v88, v82, v83
	v_cvt_pk_bf16_f32 v89, v84, v85
	v_add_u32_e32 v166, 0x10100, v0
	global_store_dwordx4 v166, v[86:89], s[98:99]
	v_cvt_pk_bf16_f32 v78, v78, v79
	v_cvt_pk_bf16_f32 v79, v80, v81
	v_cvt_pk_bf16_f32 v80, v74, v75
	v_cvt_pk_bf16_f32 v81, v76, v77
	v_add_u32_e32 v167, 0x18000, v0
	global_store_dwordx4 v167, v[78:81], s[98:99]
	v_cvt_pk_bf16_f32 v70, v70, v71
	v_cvt_pk_bf16_f32 v71, v72, v73
	v_cvt_pk_bf16_f32 v72, v66, v67
	v_cvt_pk_bf16_f32 v73, v68, v69
	v_add_u32_e32 v168, 0x18100, v0
	global_store_dwordx4 v168, v[70:73], s[98:99]
	v_cvt_pk_bf16_f32 v62, v62, v63
	v_cvt_pk_bf16_f32 v63, v64, v65
	v_cvt_pk_bf16_f32 v64, v58, v59
	v_cvt_pk_bf16_f32 v65, v60, v61
	v_add_u32_e32 v169, 0x40000, v0
	global_store_dwordx4 v169, v[62:65], s[98:99]
	v_cvt_pk_bf16_f32 v54, v54, v55
	v_cvt_pk_bf16_f32 v55, v56, v57
	v_cvt_pk_bf16_f32 v56, v50, v51
	v_cvt_pk_bf16_f32 v57, v52, v53
	v_add_u32_e32 v170, 0x40100, v0
	global_store_dwordx4 v170, v[54:57], s[98:99]
	v_cvt_pk_bf16_f32 v46, v46, v47
	v_cvt_pk_bf16_f32 v47, v48, v49
	v_cvt_pk_bf16_f32 v48, v42, v43
	v_cvt_pk_bf16_f32 v49, v44, v45
	v_add_u32_e32 v171, 0x48000, v0
	global_store_dwordx4 v171, v[46:49], s[98:99]
	v_cvt_pk_bf16_f32 v38, v38, v39
	v_cvt_pk_bf16_f32 v39, v40, v41
	v_cvt_pk_bf16_f32 v40, v34, v35
	v_cvt_pk_bf16_f32 v41, v36, v37
	v_add_u32_e32 v158, 0x48100, v0
	global_store_dwordx4 v158, v[38:41], s[98:99]
	v_cvt_pk_bf16_f32 v30, v30, v31
	v_cvt_pk_bf16_f32 v31, v32, v33
	v_cvt_pk_bf16_f32 v32, v26, v27
	v_cvt_pk_bf16_f32 v33, v28, v29
	v_add_u32_e32 v159, 0x50000, v0
	global_store_dwordx4 v159, v[30:33], s[98:99]
	v_cvt_pk_bf16_f32 v22, v22, v23
	v_cvt_pk_bf16_f32 v23, v24, v25
	v_cvt_pk_bf16_f32 v24, v18, v19
	v_cvt_pk_bf16_f32 v25, v20, v21
	v_add_u32_e32 v164, 0x50100, v0
	global_store_dwordx4 v164, v[22:25], s[98:99]
	v_cvt_pk_bf16_f32 v14, v14, v15
	v_cvt_pk_bf16_f32 v15, v16, v17
	v_cvt_pk_bf16_f32 v16, v10, v11
	v_cvt_pk_bf16_f32 v17, v12, v13
	v_add_u32_e32 v165, 0x58000, v0
	global_store_dwordx4 v165, v[14:17], s[98:99]
	v_cvt_pk_bf16_f32 v6, v6, v7
	v_cvt_pk_bf16_f32 v7, v8, v9
	v_cvt_pk_bf16_f32 v8, v2, v3
	v_cvt_pk_bf16_f32 v9, v4, v5
	v_add_u32_e32 v166, 0x58100, v0
	global_store_dwordx4 v166, v[6:9], s[98:99]
	s_branch .Lpd_done
.Lpd_vtd:
	s_add_u32 s98, s98, 0xb500000
	s_addc_u32 s99, s99, 0
	v_and_b32_e32 v158, 0xfff, v0
	v_lshrrev_b32_e32 v0, 12, v0
	v_lshlrev_b32_e32 v0, 2, v0
	s_sub_i32 s22, s2, 13
	s_lshl_b32 s22, s22, 1
	v_add_u32_e32 v0, s22, v0
	v_lshlrev_b32_e32 v0, 7, v0
	v_add_u32_e32 v0, v0, v161
	v_lshlrev_b32_e32 v0, 13, v0
	v_lshl_add_u32 v0, v158, 1, v0
	v_add_u32_e32 v158, 0x2000, v0
	v_add_u32_e32 v159, 0x4000, v0
	v_add_u32_e32 v163, 0x6000, v0
	v_add_u32_e32 v164, 0x8000, v0
	v_add_u32_e32 v165, 0xa000, v0
	v_add_u32_e32 v166, 0xc000, v0
	v_add_u32_e32 v167, 0xe000, v0
	v_cvt_pk_bf16_f32 v126, v126, v127
	v_cvt_pk_bf16_f32 v127, v128, v129
	v_cvt_pk_bf16_f32 v128, v122, v123
	v_cvt_pk_bf16_f32 v129, v124, v125
	global_store_short v0, v126, s[98:99]
	global_store_short_d16_hi v158, v126, s[98:99]
	global_store_short v159, v127, s[98:99]
	global_store_short_d16_hi v163, v127, s[98:99]
	global_store_short v164, v128, s[98:99]
	global_store_short_d16_hi v165, v128, s[98:99]
	global_store_short v166, v129, s[98:99]
	global_store_short_d16_hi v167, v129, s[98:99]
	v_cvt_pk_bf16_f32 v110, v110, v111
	v_cvt_pk_bf16_f32 v111, v112, v113
	v_cvt_pk_bf16_f32 v112, v106, v107
	v_cvt_pk_bf16_f32 v113, v108, v109
	global_store_short v0, v110, s[98:99] offset:32
	global_store_short_d16_hi v158, v110, s[98:99] offset:32
	global_store_short v159, v111, s[98:99] offset:32
	global_store_short_d16_hi v163, v111, s[98:99] offset:32
	global_store_short v164, v112, s[98:99] offset:32
	global_store_short_d16_hi v165, v112, s[98:99] offset:32
	global_store_short v166, v113, s[98:99] offset:32
	global_store_short_d16_hi v167, v113, s[98:99] offset:32
	v_cvt_pk_bf16_f32 v94, v94, v95
	v_cvt_pk_bf16_f32 v95, v96, v97
	v_cvt_pk_bf16_f32 v96, v90, v91
	v_cvt_pk_bf16_f32 v97, v92, v93
	global_store_short v0, v94, s[98:99] offset:64
	global_store_short_d16_hi v158, v94, s[98:99] offset:64
	global_store_short v159, v95, s[98:99] offset:64
	global_store_short_d16_hi v163, v95, s[98:99] offset:64
	global_store_short v164, v96, s[98:99] offset:64
	global_store_short_d16_hi v165, v96, s[98:99] offset:64
	global_store_short v166, v97, s[98:99] offset:64
	global_store_short_d16_hi v167, v97, s[98:99] offset:64
; __device__ __forceinline__ bf16_t f2bf(float f) { return (bf16_t)(cvt_pk_bf16(f, 0.f) & 0xffffu); }
;     __device__ __forceinline__ void emit(int row, int pn, int col0, float* v) const {
;     ...
;             else if (pn < 15) { const int cv = col0 - 3328, hh = cv >> 7, dv = cv & 127, bl = row >> 12, s = row & 4095;
;                 bf16_t* p = (bf16_t*)(ws + WS_VTD) + ((size_t)(bl * 4 + hh) * 128 + dv) * S + s;
; #pragma unroll
;                 for (int j = 0; j < 8; ++j) p[(size_t)j * S] = f2bf(v[j]); }
	v_cvt_pk_bf16_f32 v78, v78, v79
	v_cvt_pk_bf16_f32 v79, v80, v81
	v_cvt_pk_bf16_f32 v80, v74, v75
	v_cvt_pk_bf16_f32 v81, v76, v77
	global_store_short v0, v78, s[98:99] offset:96
	global_store_short_d16_hi v158, v78, s[98:99] offset:96
	global_store_short v159, v79, s[98:99] offset:96
	global_store_short_d16_hi v163, v79, s[98:99] offset:96
	global_store_short v164, v80, s[98:99] offset:96
	global_store_short_d16_hi v165, v80, s[98:99] offset:96
	global_store_short v166, v81, s[98:99] offset:96
	global_store_short_d16_hi v167, v81, s[98:99] offset:96
	v_cvt_pk_bf16_f32 v62, v62, v63
	v_cvt_pk_bf16_f32 v63, v64, v65
	v_cvt_pk_bf16_f32 v64, v58, v59
	v_cvt_pk_bf16_f32 v65, v60, v61
	global_store_short v0, v62, s[98:99] offset:256
	global_store_short_d16_hi v158, v62, s[98:99] offset:256
	global_store_short v159, v63, s[98:99] offset:256
	global_store_short_d16_hi v163, v63, s[98:99] offset:256
	global_store_short v164, v64, s[98:99] offset:256
	global_store_short_d16_hi v165, v64, s[98:99] offset:256
	global_store_short v166, v65, s[98:99] offset:256
	global_store_short_d16_hi v167, v65, s[98:99] offset:256
	v_cvt_pk_bf16_f32 v46, v46, v47
	v_cvt_pk_bf16_f32 v47, v48, v49
	v_cvt_pk_bf16_f32 v48, v42, v43
	v_cvt_pk_bf16_f32 v49, v44, v45
	global_store_short v0, v46, s[98:99] offset:288
	global_store_short_d16_hi v158, v46, s[98:99] offset:288
	global_store_short v159, v47, s[98:99] offset:288
	global_store_short_d16_hi v163, v47, s[98:99] offset:288
	global_store_short v164, v48, s[98:99] offset:288
	global_store_short_d16_hi v165, v48, s[98:99] offset:288
	global_store_short v166, v49, s[98:99] offset:288
	global_store_short_d16_hi v167, v49, s[98:99] offset:288
	v_cvt_pk_bf16_f32 v30, v30, v31
	v_cvt_pk_bf16_f32 v31, v32, v33
	v_cvt_pk_bf16_f32 v32, v26, v27
	v_cvt_pk_bf16_f32 v33, v28, v29
	global_store_short v0, v30, s[98:99] offset:320
	global_store_short_d16_hi v158, v30, s[98:99] offset:320
	global_store_short v159, v31, s[98:99] offset:320
	global_store_short_d16_hi v163, v31, s[98:99] offset:320
	global_store_short v164, v32, s[98:99] offset:320
	global_store_short_d16_hi v165, v32, s[98:99] offset:320
	global_store_short v166, v33, s[98:99] offset:320
	global_store_short_d16_hi v167, v33, s[98:99] offset:320
	v_cvt_pk_bf16_f32 v14, v14, v15
	v_cvt_pk_bf16_f32 v15, v16, v17
	v_cvt_pk_bf16_f32 v16, v10, v11
	v_cvt_pk_bf16_f32 v17, v12, v13
	global_store_short v0, v14, s[98:99] offset:352
	global_store_short_d16_hi v158, v14, s[98:99] offset:352
	global_store_short v159, v15, s[98:99] offset:352
	global_store_short_d16_hi v163, v15, s[98:99] offset:352
	global_store_short v164, v16, s[98:99] offset:352
	global_store_short_d16_hi v165, v16, s[98:99] offset:352
	global_store_short v166, v17, s[98:99] offset:352
	global_store_short_d16_hi v167, v17, s[98:99] offset:352
	v_add_u32_e32 v0, 0x100000, v0
	v_add_u32_e32 v158, 0x100000, v158
	v_add_u32_e32 v159, 0x100000, v159
	v_add_u32_e32 v163, 0x100000, v163
	v_add_u32_e32 v164, 0x100000, v164
	v_add_u32_e32 v165, 0x100000, v165
	v_add_u32_e32 v166, 0x100000, v166
	v_add_u32_e32 v167, 0x100000, v167
	v_cvt_pk_bf16_f32 v118, v118, v119
	v_cvt_pk_bf16_f32 v119, v120, v121
	v_cvt_pk_bf16_f32 v120, v114, v115
	v_cvt_pk_bf16_f32 v121, v116, v117
	global_store_short v0, v118, s[98:99]
	global_store_short_d16_hi v158, v118, s[98:99]
	global_store_short v159, v119, s[98:99]
	global_store_short_d16_hi v163, v119, s[98:99]
	global_store_short v164, v120, s[98:99]
	global_store_short_d16_hi v165, v120, s[98:99]
	global_store_short v166, v121, s[98:99]
	global_store_short_d16_hi v167, v121, s[98:99]
	v_cvt_pk_bf16_f32 v102, v102, v103
	v_cvt_pk_bf16_f32 v103, v104, v105
	v_cvt_pk_bf16_f32 v104, v98, v99
	v_cvt_pk_bf16_f32 v105, v100, v101
	global_store_short v0, v102, s[98:99] offset:32
	global_store_short_d16_hi v158, v102, s[98:99] offset:32
	global_store_short v159, v103, s[98:99] offset:32
	global_store_short_d16_hi v163, v103, s[98:99] offset:32
	global_store_short v164, v104, s[98:99] offset:32
	global_store_short_d16_hi v165, v104, s[98:99] offset:32
	global_store_short v166, v105, s[98:99] offset:32
	global_store_short_d16_hi v167, v105, s[98:99] offset:32
	v_cvt_pk_bf16_f32 v86, v86, v87
	v_cvt_pk_bf16_f32 v87, v88, v89
	v_cvt_pk_bf16_f32 v88, v82, v83
	v_cvt_pk_bf16_f32 v89, v84, v85
	global_store_short v0, v86, s[98:99] offset:64
	global_store_short_d16_hi v158, v86, s[98:99] offset:64
	global_store_short v159, v87, s[98:99] offset:64
	global_store_short_d16_hi v163, v87, s[98:99] offset:64
	global_store_short v164, v88, s[98:99] offset:64
	global_store_short_d16_hi v165, v88, s[98:99] offset:64
	global_store_short v166, v89, s[98:99] offset:64
	global_store_short_d16_hi v167, v89, s[98:99] offset:64
	v_cvt_pk_bf16_f32 v70, v70, v71
	v_cvt_pk_bf16_f32 v71, v72, v73
	v_cvt_pk_bf16_f32 v72, v66, v67
	v_cvt_pk_bf16_f32 v73, v68, v69
	global_store_short v0, v70, s[98:99] offset:96
	global_store_short_d16_hi v158, v70, s[98:99] offset:96
	global_store_short v159, v71, s[98:99] offset:96
	global_store_short_d16_hi v163, v71, s[98:99] offset:96
	global_store_short v164, v72, s[98:99] offset:96
	global_store_short_d16_hi v165, v72, s[98:99] offset:96
	global_store_short v166, v73, s[98:99] offset:96
	global_store_short_d16_hi v167, v73, s[98:99] offset:96
	v_cvt_pk_bf16_f32 v54, v54, v55
	v_cvt_pk_bf16_f32 v55, v56, v57
	v_cvt_pk_bf16_f32 v56, v50, v51
	v_cvt_pk_bf16_f32 v57, v52, v53
	global_store_short v0, v54, s[98:99] offset:256
	global_store_short_d16_hi v158, v54, s[98:99] offset:256
	global_store_short v159, v55, s[98:99] offset:256
	global_store_short_d16_hi v163, v55, s[98:99] offset:256
; __device__ __forceinline__ bf16_t f2bf(float f) { return (bf16_t)(cvt_pk_bf16(f, 0.f) & 0xffffu); }
; __device__ __forceinline__ float sigmoidf_(float x) { return __builtin_amdgcn_rcpf(1.f + __expf(-x)); }
;     __device__ __forceinline__ void emit(int row, int pn, int col0, float* v) const {
;     ...
;             else if (pn < 15) { const int cv = col0 - 3328, hh = cv >> 7, dv = cv & 127, bl = row >> 12, s = row & 4095;
;                 bf16_t* p = (bf16_t*)(ws + WS_VTD) + ((size_t)(bl * 4 + hh) * 128 + dv) * S + s;
; #pragma unroll
;                 for (int j = 0; j < 8; ++j) p[(size_t)j * S] = f2bf(v[j]); }
;             else { const int cg_ = col0 - 3840; const f32x4 b0 = ldg<f32x4>(f0 + cg_), b1 = ldg<f32x4>(f0 + cg_ + 4);
;                 v[0] = sigmoidf_(v[0] + b0.x); v[1] = sigmoidf_(v[1] + b0.y); v[2] = sigmoidf_(v[2] + b0.z); v[3] = sigmoidf_(v[3] + b0.w);
;                 v[4] = sigmoidf_(v[4] + b1.x); v[5] = sigmoidf_(v[5] + b1.y); v[6] = sigmoidf_(v[6] + b1.z); v[7] = sigmoidf_(v[7] + b1.w);
;                 store8((bf16_t*)(ws + WS_GATE) + (size_t)row * GT_COLS + cg_, v); }
	global_store_short v164, v56, s[98:99] offset:256
	global_store_short_d16_hi v165, v56, s[98:99] offset:256
	global_store_short v166, v57, s[98:99] offset:256
	global_store_short_d16_hi v167, v57, s[98:99] offset:256
	v_cvt_pk_bf16_f32 v38, v38, v39
	v_cvt_pk_bf16_f32 v39, v40, v41
	v_cvt_pk_bf16_f32 v40, v34, v35
	v_cvt_pk_bf16_f32 v41, v36, v37
	global_store_short v0, v38, s[98:99] offset:288
	global_store_short_d16_hi v158, v38, s[98:99] offset:288
	global_store_short v159, v39, s[98:99] offset:288
	global_store_short_d16_hi v163, v39, s[98:99] offset:288
	global_store_short v164, v40, s[98:99] offset:288
	global_store_short_d16_hi v165, v40, s[98:99] offset:288
	global_store_short v166, v41, s[98:99] offset:288
	global_store_short_d16_hi v167, v41, s[98:99] offset:288
	v_cvt_pk_bf16_f32 v22, v22, v23
	v_cvt_pk_bf16_f32 v23, v24, v25
	v_cvt_pk_bf16_f32 v24, v18, v19
	v_cvt_pk_bf16_f32 v25, v20, v21
	global_store_short v0, v22, s[98:99] offset:320
	global_store_short_d16_hi v158, v22, s[98:99] offset:320
	global_store_short v159, v23, s[98:99] offset:320
	global_store_short_d16_hi v163, v23, s[98:99] offset:320
	global_store_short v164, v24, s[98:99] offset:320
	global_store_short_d16_hi v165, v24, s[98:99] offset:320
	global_store_short v166, v25, s[98:99] offset:320
	global_store_short_d16_hi v167, v25, s[98:99] offset:320
	v_cvt_pk_bf16_f32 v6, v6, v7
	v_cvt_pk_bf16_f32 v7, v8, v9
	v_cvt_pk_bf16_f32 v8, v2, v3
	v_cvt_pk_bf16_f32 v9, v4, v5
	global_store_short v0, v6, s[98:99] offset:352
	global_store_short_d16_hi v158, v6, s[98:99] offset:352
	global_store_short v159, v7, s[98:99] offset:352
	global_store_short_d16_hi v163, v7, s[98:99] offset:352
	global_store_short v164, v8, s[98:99] offset:352
	global_store_short_d16_hi v165, v8, s[98:99] offset:352
	global_store_short v166, v9, s[98:99] offset:352
	global_store_short_d16_hi v167, v9, s[98:99] offset:352
.Lpd_done:
	s_mov_b32 s22, 1
	s_mov_b64 s[2:3], 0
	s_and_b64 vcc, exec, s[38:39]
	s_cbranch_vccz .LBB0_229
	s_branch .Lpd_tail
.Lpd_tramp:
	s_branch .LBB0_1525
.Lgt_epi:
	v_lshl_or_b32 v163, s2, 8, v161
	v_add_u32_e32 v0, 0xfffff100, v163
	v_lshlrev_b32_e32 v226, 1, v0
	v_mov_b32_e32 v227, 0
	v_lshlrev_b32_e32 v0, 2, v0
	global_load_dwordx4 v[210:213], v0, s[6:7]
	global_load_dwordx4 v[214:217], v0, s[6:7] offset:16
	global_load_dwordx4 v[218:221], v0, s[6:7] offset:512
	global_load_dwordx4 v[222:225], v0, s[6:7] offset:528
	s_waitcnt vmcnt(0)
	v_pk_add_f32 v[126:127], v[126:127], v[210:211]
	v_pk_add_f32 v[128:129], v[128:129], v[212:213]
	v_pk_add_f32 v[122:123], v[122:123], v[214:215]
	v_pk_add_f32 v[124:125], v[124:125], v[216:217]
	v_mul_f32_e32 v126, 0xbfb8aa3b, v126
	v_mul_f32_e32 v127, 0xbfb8aa3b, v127
	v_mul_f32_e32 v128, 0xbfb8aa3b, v128
	v_mul_f32_e32 v129, 0xbfb8aa3b, v129
	v_mul_f32_e32 v122, 0xbfb8aa3b, v122
	v_mul_f32_e32 v123, 0xbfb8aa3b, v123
	v_mul_f32_e32 v124, 0xbfb8aa3b, v124
	v_mul_f32_e32 v125, 0xbfb8aa3b, v125
	v_exp_f32_e32 v126, v126
	v_exp_f32_e32 v127, v127
	v_exp_f32_e32 v128, v128
	v_exp_f32_e32 v129, v129
	v_exp_f32_e32 v122, v122
	v_exp_f32_e32 v123, v123
	v_exp_f32_e32 v124, v124
	v_exp_f32_e32 v125, v125
	v_add_f32_e32 v126, 1.0, v126
	v_add_f32_e32 v127, 1.0, v127
	v_add_f32_e32 v128, 1.0, v128
	v_add_f32_e32 v129, 1.0, v129
	v_add_f32_e32 v122, 1.0, v122
	v_add_f32_e32 v123, 1.0, v123
	v_add_f32_e32 v124, 1.0, v124
	v_add_f32_e32 v125, 1.0, v125
	v_rcp_f32_e32 v126, v126
	v_rcp_f32_e32 v127, v127
	v_rcp_f32_e32 v128, v128
	v_rcp_f32_e32 v129, v129
	v_rcp_f32_e32 v122, v122
	v_rcp_f32_e32 v123, v123
	v_rcp_f32_e32 v124, v124
	v_rcp_f32_e32 v125, v125
	s_nop 0
	v_cvt_pk_bf16_f32 v228, v126, v127
	v_cvt_pk_bf16_f32 v229, v128, v129
	v_cvt_pk_bf16_f32 v230, v122, v123
	v_cvt_pk_bf16_f32 v231, v124, v125
	v_lshl_add_u64 v[236:237], v[138:139], 0, v[226:227]
	global_store_dwordx4 v[236:237], v[228:231], off
	v_pk_add_f32 v[118:119], v[118:119], v[218:219]
	v_pk_add_f32 v[120:121], v[120:121], v[220:221]
	v_pk_add_f32 v[114:115], v[114:115], v[222:223]
	v_pk_add_f32 v[116:117], v[116:117], v[224:225]
	v_mul_f32_e32 v118, 0xbfb8aa3b, v118
	v_mul_f32_e32 v119, 0xbfb8aa3b, v119
	v_mul_f32_e32 v120, 0xbfb8aa3b, v120
	v_mul_f32_e32 v121, 0xbfb8aa3b, v121
	v_mul_f32_e32 v114, 0xbfb8aa3b, v114
	v_mul_f32_e32 v115, 0xbfb8aa3b, v115
	v_mul_f32_e32 v116, 0xbfb8aa3b, v116
	v_mul_f32_e32 v117, 0xbfb8aa3b, v117
	v_exp_f32_e32 v118, v118
	v_exp_f32_e32 v119, v119
	v_exp_f32_e32 v120, v120
	v_exp_f32_e32 v121, v121
	v_exp_f32_e32 v114, v114
	v_exp_f32_e32 v115, v115
	v_exp_f32_e32 v116, v116
	v_exp_f32_e32 v117, v117
	v_add_f32_e32 v118, 1.0, v118
	v_add_f32_e32 v119, 1.0, v119
	v_add_f32_e32 v120, 1.0, v120
	v_add_f32_e32 v121, 1.0, v121
	v_add_f32_e32 v114, 1.0, v114
	v_add_f32_e32 v115, 1.0, v115
	v_add_f32_e32 v116, 1.0, v116
	v_add_f32_e32 v117, 1.0, v117
	v_rcp_f32_e32 v118, v118
	v_rcp_f32_e32 v119, v119
	v_rcp_f32_e32 v120, v120
	v_rcp_f32_e32 v121, v121
	v_rcp_f32_e32 v114, v114
	v_rcp_f32_e32 v115, v115
	v_rcp_f32_e32 v116, v116
	v_rcp_f32_e32 v117, v117
	s_nop 0
	v_cvt_pk_bf16_f32 v232, v118, v119
	v_cvt_pk_bf16_f32 v233, v120, v121
	v_cvt_pk_bf16_f32 v234, v114, v115
	v_cvt_pk_bf16_f32 v235, v116, v117
	v_lshl_add_u64 v[238:239], v[138:139], 0, v[226:227]
	global_store_dwordx4 v[238:239], v[232:235], off offset:256
	v_pk_add_f32 v[110:111], v[110:111], v[210:211]
	v_pk_add_f32 v[112:113], v[112:113], v[212:213]
	v_pk_add_f32 v[106:107], v[106:107], v[214:215]
	v_pk_add_f32 v[108:109], v[108:109], v[216:217]
	v_mul_f32_e32 v110, 0xbfb8aa3b, v110
	v_mul_f32_e32 v111, 0xbfb8aa3b, v111
	v_mul_f32_e32 v112, 0xbfb8aa3b, v112
	v_mul_f32_e32 v113, 0xbfb8aa3b, v113
; __device__ __forceinline__ float sigmoidf_(float x) { return __builtin_amdgcn_rcpf(1.f + __expf(-x)); }
;     __device__ __forceinline__ void emit(int row, int pn, int col0, float* v) const {
;     ...
;             else { const int cg_ = col0 - 3840; const f32x4 b0 = ldg<f32x4>(f0 + cg_), b1 = ldg<f32x4>(f0 + cg_ + 4);
;                 v[0] = sigmoidf_(v[0] + b0.x); v[1] = sigmoidf_(v[1] + b0.y); v[2] = sigmoidf_(v[2] + b0.z); v[3] = sigmoidf_(v[3] + b0.w);
;                 v[4] = sigmoidf_(v[4] + b1.x); v[5] = sigmoidf_(v[5] + b1.y); v[6] = sigmoidf_(v[6] + b1.z); v[7] = sigmoidf_(v[7] + b1.w);
;                 store8((bf16_t*)(ws + WS_GATE) + (size_t)row * GT_COLS + cg_, v); }
	v_mul_f32_e32 v106, 0xbfb8aa3b, v106
	v_mul_f32_e32 v107, 0xbfb8aa3b, v107
	v_mul_f32_e32 v108, 0xbfb8aa3b, v108
	v_mul_f32_e32 v109, 0xbfb8aa3b, v109
	v_exp_f32_e32 v110, v110
	v_exp_f32_e32 v111, v111
	v_exp_f32_e32 v112, v112
	v_exp_f32_e32 v113, v113
	v_exp_f32_e32 v106, v106
	v_exp_f32_e32 v107, v107
	v_exp_f32_e32 v108, v108
	v_exp_f32_e32 v109, v109
	v_add_f32_e32 v110, 1.0, v110
	v_add_f32_e32 v111, 1.0, v111
	v_add_f32_e32 v112, 1.0, v112
	v_add_f32_e32 v113, 1.0, v113
	v_add_f32_e32 v106, 1.0, v106
	v_add_f32_e32 v107, 1.0, v107
	v_add_f32_e32 v108, 1.0, v108
	v_add_f32_e32 v109, 1.0, v109
	v_rcp_f32_e32 v110, v110
	v_rcp_f32_e32 v111, v111
	v_rcp_f32_e32 v112, v112
	v_rcp_f32_e32 v113, v113
	v_rcp_f32_e32 v106, v106
	v_rcp_f32_e32 v107, v107
	v_rcp_f32_e32 v108, v108
	v_rcp_f32_e32 v109, v109
	s_nop 0
	v_cvt_pk_bf16_f32 v228, v110, v111
	v_cvt_pk_bf16_f32 v229, v112, v113
	v_cvt_pk_bf16_f32 v230, v106, v107
	v_cvt_pk_bf16_f32 v231, v108, v109
	v_lshl_add_u64 v[236:237], v[140:141], 0, v[226:227]
	global_store_dwordx4 v[236:237], v[228:231], off
	v_pk_add_f32 v[102:103], v[102:103], v[218:219]
	v_pk_add_f32 v[104:105], v[104:105], v[220:221]
	v_pk_add_f32 v[98:99], v[98:99], v[222:223]
	v_pk_add_f32 v[100:101], v[100:101], v[224:225]
	v_mul_f32_e32 v102, 0xbfb8aa3b, v102
	v_mul_f32_e32 v103, 0xbfb8aa3b, v103
	v_mul_f32_e32 v104, 0xbfb8aa3b, v104
	v_mul_f32_e32 v105, 0xbfb8aa3b, v105
	v_mul_f32_e32 v98, 0xbfb8aa3b, v98
	v_mul_f32_e32 v99, 0xbfb8aa3b, v99
	v_mul_f32_e32 v100, 0xbfb8aa3b, v100
	v_mul_f32_e32 v101, 0xbfb8aa3b, v101
	v_exp_f32_e32 v102, v102
	v_exp_f32_e32 v103, v103
	v_exp_f32_e32 v104, v104
	v_exp_f32_e32 v105, v105
	v_exp_f32_e32 v98, v98
	v_exp_f32_e32 v99, v99
	v_exp_f32_e32 v100, v100
	v_exp_f32_e32 v101, v101
	v_add_f32_e32 v102, 1.0, v102
	v_add_f32_e32 v103, 1.0, v103
	v_add_f32_e32 v104, 1.0, v104
	v_add_f32_e32 v105, 1.0, v105
	v_add_f32_e32 v98, 1.0, v98
	v_add_f32_e32 v99, 1.0, v99
	v_add_f32_e32 v100, 1.0, v100
	v_add_f32_e32 v101, 1.0, v101
	v_rcp_f32_e32 v102, v102
	v_rcp_f32_e32 v103, v103
	v_rcp_f32_e32 v104, v104
	v_rcp_f32_e32 v105, v105
	v_rcp_f32_e32 v98, v98
	v_rcp_f32_e32 v99, v99
	v_rcp_f32_e32 v100, v100
	v_rcp_f32_e32 v101, v101
	s_nop 0
	v_cvt_pk_bf16_f32 v232, v102, v103
	v_cvt_pk_bf16_f32 v233, v104, v105
	v_cvt_pk_bf16_f32 v234, v98, v99
	v_cvt_pk_bf16_f32 v235, v100, v101
	v_lshl_add_u64 v[238:239], v[140:141], 0, v[226:227]
	global_store_dwordx4 v[238:239], v[232:235], off offset:256
	v_pk_add_f32 v[94:95], v[94:95], v[210:211]
	v_pk_add_f32 v[96:97], v[96:97], v[212:213]
	v_pk_add_f32 v[90:91], v[90:91], v[214:215]
	v_pk_add_f32 v[92:93], v[92:93], v[216:217]
	v_mul_f32_e32 v94, 0xbfb8aa3b, v94
	v_mul_f32_e32 v95, 0xbfb8aa3b, v95
	v_mul_f32_e32 v96, 0xbfb8aa3b, v96
	v_mul_f32_e32 v97, 0xbfb8aa3b, v97
	v_mul_f32_e32 v90, 0xbfb8aa3b, v90
	v_mul_f32_e32 v91, 0xbfb8aa3b, v91
	v_mul_f32_e32 v92, 0xbfb8aa3b, v92
	v_mul_f32_e32 v93, 0xbfb8aa3b, v93
	v_exp_f32_e32 v94, v94
	v_exp_f32_e32 v95, v95
	v_exp_f32_e32 v96, v96
	v_exp_f32_e32 v97, v97
	v_exp_f32_e32 v90, v90
	v_exp_f32_e32 v91, v91
	v_exp_f32_e32 v92, v92
	v_exp_f32_e32 v93, v93
	v_add_f32_e32 v94, 1.0, v94
	v_add_f32_e32 v95, 1.0, v95
	v_add_f32_e32 v96, 1.0, v96
	v_add_f32_e32 v97, 1.0, v97
	v_add_f32_e32 v90, 1.0, v90
	v_add_f32_e32 v91, 1.0, v91
	v_add_f32_e32 v92, 1.0, v92
	v_add_f32_e32 v93, 1.0, v93
	v_rcp_f32_e32 v94, v94
	v_rcp_f32_e32 v95, v95
	v_rcp_f32_e32 v96, v96
	v_rcp_f32_e32 v97, v97
	v_rcp_f32_e32 v90, v90
	v_rcp_f32_e32 v91, v91
	v_rcp_f32_e32 v92, v92
	v_rcp_f32_e32 v93, v93
	s_nop 0
	v_cvt_pk_bf16_f32 v228, v94, v95
	v_cvt_pk_bf16_f32 v229, v96, v97
	v_cvt_pk_bf16_f32 v230, v90, v91
	v_cvt_pk_bf16_f32 v231, v92, v93
	v_lshl_add_u64 v[236:237], v[142:143], 0, v[226:227]
	global_store_dwordx4 v[236:237], v[228:231], off
	v_pk_add_f32 v[86:87], v[86:87], v[218:219]
	v_pk_add_f32 v[88:89], v[88:89], v[220:221]
	v_pk_add_f32 v[82:83], v[82:83], v[222:223]
	v_pk_add_f32 v[84:85], v[84:85], v[224:225]
	v_mul_f32_e32 v86, 0xbfb8aa3b, v86
	v_mul_f32_e32 v87, 0xbfb8aa3b, v87
	v_mul_f32_e32 v88, 0xbfb8aa3b, v88
	v_mul_f32_e32 v89, 0xbfb8aa3b, v89
	v_mul_f32_e32 v82, 0xbfb8aa3b, v82
	v_mul_f32_e32 v83, 0xbfb8aa3b, v83
	v_mul_f32_e32 v84, 0xbfb8aa3b, v84
	v_mul_f32_e32 v85, 0xbfb8aa3b, v85
	v_exp_f32_e32 v86, v86
	v_exp_f32_e32 v87, v87
	v_exp_f32_e32 v88, v88
	v_exp_f32_e32 v89, v89
	v_exp_f32_e32 v82, v82
	v_exp_f32_e32 v83, v83
	v_exp_f32_e32 v84, v84
	v_exp_f32_e32 v85, v85
	v_add_f32_e32 v86, 1.0, v86
	v_add_f32_e32 v87, 1.0, v87
	v_add_f32_e32 v88, 1.0, v88
	v_add_f32_e32 v89, 1.0, v89
	v_add_f32_e32 v82, 1.0, v82
	v_add_f32_e32 v83, 1.0, v83
	v_add_f32_e32 v84, 1.0, v84
	v_add_f32_e32 v85, 1.0, v85
	v_rcp_f32_e32 v86, v86
	v_rcp_f32_e32 v87, v87
	v_rcp_f32_e32 v88, v88
	v_rcp_f32_e32 v89, v89
	v_rcp_f32_e32 v82, v82
	v_rcp_f32_e32 v83, v83
	v_rcp_f32_e32 v84, v84
	v_rcp_f32_e32 v85, v85
	s_nop 0
	v_cvt_pk_bf16_f32 v232, v86, v87
	v_cvt_pk_bf16_f32 v233, v88, v89
	v_cvt_pk_bf16_f32 v234, v82, v83
	v_cvt_pk_bf16_f32 v235, v84, v85
	v_lshl_add_u64 v[238:239], v[142:143], 0, v[226:227]
	global_store_dwordx4 v[238:239], v[232:235], off offset:256
	v_pk_add_f32 v[78:79], v[78:79], v[210:211]
	v_pk_add_f32 v[80:81], v[80:81], v[212:213]
	v_pk_add_f32 v[74:75], v[74:75], v[214:215]
	v_pk_add_f32 v[76:77], v[76:77], v[216:217]
	v_mul_f32_e32 v78, 0xbfb8aa3b, v78
	v_mul_f32_e32 v79, 0xbfb8aa3b, v79
	v_mul_f32_e32 v80, 0xbfb8aa3b, v80
	v_mul_f32_e32 v81, 0xbfb8aa3b, v81
	v_mul_f32_e32 v74, 0xbfb8aa3b, v74
	v_mul_f32_e32 v75, 0xbfb8aa3b, v75
	v_mul_f32_e32 v76, 0xbfb8aa3b, v76
	v_mul_f32_e32 v77, 0xbfb8aa3b, v77
; __device__ __forceinline__ float sigmoidf_(float x) { return __builtin_amdgcn_rcpf(1.f + __expf(-x)); }
;     __device__ __forceinline__ void emit(int row, int pn, int col0, float* v) const {
;     ...
;             else { const int cg_ = col0 - 3840; const f32x4 b0 = ldg<f32x4>(f0 + cg_), b1 = ldg<f32x4>(f0 + cg_ + 4);
;                 v[0] = sigmoidf_(v[0] + b0.x); v[1] = sigmoidf_(v[1] + b0.y); v[2] = sigmoidf_(v[2] + b0.z); v[3] = sigmoidf_(v[3] + b0.w);
;                 v[4] = sigmoidf_(v[4] + b1.x); v[5] = sigmoidf_(v[5] + b1.y); v[6] = sigmoidf_(v[6] + b1.z); v[7] = sigmoidf_(v[7] + b1.w);
;                 store8((bf16_t*)(ws + WS_GATE) + (size_t)row * GT_COLS + cg_, v); }
	v_exp_f32_e32 v78, v78
	v_exp_f32_e32 v79, v79
	v_exp_f32_e32 v80, v80
	v_exp_f32_e32 v81, v81
	v_exp_f32_e32 v74, v74
	v_exp_f32_e32 v75, v75
	v_exp_f32_e32 v76, v76
	v_exp_f32_e32 v77, v77
	v_add_f32_e32 v78, 1.0, v78
	v_add_f32_e32 v79, 1.0, v79
	v_add_f32_e32 v80, 1.0, v80
	v_add_f32_e32 v81, 1.0, v81
	v_add_f32_e32 v74, 1.0, v74
	v_add_f32_e32 v75, 1.0, v75
	v_add_f32_e32 v76, 1.0, v76
	v_add_f32_e32 v77, 1.0, v77
	v_rcp_f32_e32 v78, v78
	v_rcp_f32_e32 v79, v79
	v_rcp_f32_e32 v80, v80
	v_rcp_f32_e32 v81, v81
	v_rcp_f32_e32 v74, v74
	v_rcp_f32_e32 v75, v75
	v_rcp_f32_e32 v76, v76
	v_rcp_f32_e32 v77, v77
	s_nop 0
	v_cvt_pk_bf16_f32 v228, v78, v79
	v_cvt_pk_bf16_f32 v229, v80, v81
	v_cvt_pk_bf16_f32 v230, v74, v75
	v_cvt_pk_bf16_f32 v231, v76, v77
	v_lshl_add_u64 v[236:237], v[144:145], 0, v[226:227]
	global_store_dwordx4 v[236:237], v[228:231], off
	v_pk_add_f32 v[70:71], v[70:71], v[218:219]
	v_pk_add_f32 v[72:73], v[72:73], v[220:221]
	v_pk_add_f32 v[66:67], v[66:67], v[222:223]
	v_pk_add_f32 v[68:69], v[68:69], v[224:225]
	v_mul_f32_e32 v70, 0xbfb8aa3b, v70
	v_mul_f32_e32 v71, 0xbfb8aa3b, v71
	v_mul_f32_e32 v72, 0xbfb8aa3b, v72
	v_mul_f32_e32 v73, 0xbfb8aa3b, v73
	v_mul_f32_e32 v66, 0xbfb8aa3b, v66
	v_mul_f32_e32 v67, 0xbfb8aa3b, v67
	v_mul_f32_e32 v68, 0xbfb8aa3b, v68
	v_mul_f32_e32 v69, 0xbfb8aa3b, v69
	v_exp_f32_e32 v70, v70
	v_exp_f32_e32 v71, v71
	v_exp_f32_e32 v72, v72
	v_exp_f32_e32 v73, v73
	v_exp_f32_e32 v66, v66
	v_exp_f32_e32 v67, v67
	v_exp_f32_e32 v68, v68
	v_exp_f32_e32 v69, v69
	v_add_f32_e32 v70, 1.0, v70
	v_add_f32_e32 v71, 1.0, v71
	v_add_f32_e32 v72, 1.0, v72
	v_add_f32_e32 v73, 1.0, v73
	v_add_f32_e32 v66, 1.0, v66
	v_add_f32_e32 v67, 1.0, v67
	v_add_f32_e32 v68, 1.0, v68
	v_add_f32_e32 v69, 1.0, v69
	v_rcp_f32_e32 v70, v70
	v_rcp_f32_e32 v71, v71
	v_rcp_f32_e32 v72, v72
	v_rcp_f32_e32 v73, v73
	v_rcp_f32_e32 v66, v66
	v_rcp_f32_e32 v67, v67
	v_rcp_f32_e32 v68, v68
	v_rcp_f32_e32 v69, v69
	s_nop 0
	v_cvt_pk_bf16_f32 v232, v70, v71
	v_cvt_pk_bf16_f32 v233, v72, v73
	v_cvt_pk_bf16_f32 v234, v66, v67
	v_cvt_pk_bf16_f32 v235, v68, v69
	v_lshl_add_u64 v[238:239], v[144:145], 0, v[226:227]
	global_store_dwordx4 v[238:239], v[232:235], off offset:256
	v_pk_add_f32 v[62:63], v[62:63], v[210:211]
	v_pk_add_f32 v[64:65], v[64:65], v[212:213]
	v_pk_add_f32 v[58:59], v[58:59], v[214:215]
	v_pk_add_f32 v[60:61], v[60:61], v[216:217]
	v_mul_f32_e32 v62, 0xbfb8aa3b, v62
	v_mul_f32_e32 v63, 0xbfb8aa3b, v63
	v_mul_f32_e32 v64, 0xbfb8aa3b, v64
	v_mul_f32_e32 v65, 0xbfb8aa3b, v65
	v_mul_f32_e32 v58, 0xbfb8aa3b, v58
	v_mul_f32_e32 v59, 0xbfb8aa3b, v59
	v_mul_f32_e32 v60, 0xbfb8aa3b, v60
	v_mul_f32_e32 v61, 0xbfb8aa3b, v61
	v_exp_f32_e32 v62, v62
	v_exp_f32_e32 v63, v63
	v_exp_f32_e32 v64, v64
	v_exp_f32_e32 v65, v65
	v_exp_f32_e32 v58, v58
	v_exp_f32_e32 v59, v59
	v_exp_f32_e32 v60, v60
	v_exp_f32_e32 v61, v61
	v_add_f32_e32 v62, 1.0, v62
	v_add_f32_e32 v63, 1.0, v63
	v_add_f32_e32 v64, 1.0, v64
	v_add_f32_e32 v65, 1.0, v65
	v_add_f32_e32 v58, 1.0, v58
	v_add_f32_e32 v59, 1.0, v59
	v_add_f32_e32 v60, 1.0, v60
	v_add_f32_e32 v61, 1.0, v61
	v_rcp_f32_e32 v62, v62
	v_rcp_f32_e32 v63, v63
	v_rcp_f32_e32 v64, v64
	v_rcp_f32_e32 v65, v65
	v_rcp_f32_e32 v58, v58
	v_rcp_f32_e32 v59, v59
	v_rcp_f32_e32 v60, v60
	v_rcp_f32_e32 v61, v61
	s_nop 0
	v_cvt_pk_bf16_f32 v228, v62, v63
	v_cvt_pk_bf16_f32 v229, v64, v65
	v_cvt_pk_bf16_f32 v230, v58, v59
	v_cvt_pk_bf16_f32 v231, v60, v61
	v_lshl_add_u64 v[236:237], v[146:147], 0, v[226:227]
	global_store_dwordx4 v[236:237], v[228:231], off
	v_pk_add_f32 v[54:55], v[54:55], v[218:219]
	v_pk_add_f32 v[56:57], v[56:57], v[220:221]
	v_pk_add_f32 v[50:51], v[50:51], v[222:223]
	v_pk_add_f32 v[52:53], v[52:53], v[224:225]
	v_mul_f32_e32 v54, 0xbfb8aa3b, v54
	v_mul_f32_e32 v55, 0xbfb8aa3b, v55
	v_mul_f32_e32 v56, 0xbfb8aa3b, v56
	v_mul_f32_e32 v57, 0xbfb8aa3b, v57
	v_mul_f32_e32 v50, 0xbfb8aa3b, v50
	v_mul_f32_e32 v51, 0xbfb8aa3b, v51
	v_mul_f32_e32 v52, 0xbfb8aa3b, v52
	v_mul_f32_e32 v53, 0xbfb8aa3b, v53
	v_exp_f32_e32 v54, v54
	v_exp_f32_e32 v55, v55
	v_exp_f32_e32 v56, v56
	v_exp_f32_e32 v57, v57
	v_exp_f32_e32 v50, v50
	v_exp_f32_e32 v51, v51
	v_exp_f32_e32 v52, v52
	v_exp_f32_e32 v53, v53
	v_add_f32_e32 v54, 1.0, v54
	v_add_f32_e32 v55, 1.0, v55
	v_add_f32_e32 v56, 1.0, v56
	v_add_f32_e32 v57, 1.0, v57
	v_add_f32_e32 v50, 1.0, v50
	v_add_f32_e32 v51, 1.0, v51
	v_add_f32_e32 v52, 1.0, v52
	v_add_f32_e32 v53, 1.0, v53
	v_rcp_f32_e32 v54, v54
	v_rcp_f32_e32 v55, v55
	v_rcp_f32_e32 v56, v56
	v_rcp_f32_e32 v57, v57
	v_rcp_f32_e32 v50, v50
	v_rcp_f32_e32 v51, v51
	v_rcp_f32_e32 v52, v52
	v_rcp_f32_e32 v53, v53
	s_nop 0
	v_cvt_pk_bf16_f32 v232, v54, v55
	v_cvt_pk_bf16_f32 v233, v56, v57
	v_cvt_pk_bf16_f32 v234, v50, v51
	v_cvt_pk_bf16_f32 v235, v52, v53
	v_lshl_add_u64 v[238:239], v[146:147], 0, v[226:227]
	global_store_dwordx4 v[238:239], v[232:235], off offset:256
	v_pk_add_f32 v[46:47], v[46:47], v[210:211]
	v_pk_add_f32 v[48:49], v[48:49], v[212:213]
	v_pk_add_f32 v[42:43], v[42:43], v[214:215]
	v_pk_add_f32 v[44:45], v[44:45], v[216:217]
	v_mul_f32_e32 v46, 0xbfb8aa3b, v46
	v_mul_f32_e32 v47, 0xbfb8aa3b, v47
	v_mul_f32_e32 v48, 0xbfb8aa3b, v48
	v_mul_f32_e32 v49, 0xbfb8aa3b, v49
	v_mul_f32_e32 v42, 0xbfb8aa3b, v42
	v_mul_f32_e32 v43, 0xbfb8aa3b, v43
	v_mul_f32_e32 v44, 0xbfb8aa3b, v44
	v_mul_f32_e32 v45, 0xbfb8aa3b, v45
	v_exp_f32_e32 v46, v46
	v_exp_f32_e32 v47, v47
	v_exp_f32_e32 v48, v48
	v_exp_f32_e32 v49, v49
	v_exp_f32_e32 v42, v42
	v_exp_f32_e32 v43, v43
	v_exp_f32_e32 v44, v44
	v_exp_f32_e32 v45, v45
	v_add_f32_e32 v46, 1.0, v46
	v_add_f32_e32 v47, 1.0, v47
	v_add_f32_e32 v48, 1.0, v48
; __device__ __forceinline__ float sigmoidf_(float x) { return __builtin_amdgcn_rcpf(1.f + __expf(-x)); }
;     __device__ __forceinline__ void emit(int row, int pn, int col0, float* v) const {
;     ...
;             else { const int cg_ = col0 - 3840; const f32x4 b0 = ldg<f32x4>(f0 + cg_), b1 = ldg<f32x4>(f0 + cg_ + 4);
;                 v[0] = sigmoidf_(v[0] + b0.x); v[1] = sigmoidf_(v[1] + b0.y); v[2] = sigmoidf_(v[2] + b0.z); v[3] = sigmoidf_(v[3] + b0.w);
;                 v[4] = sigmoidf_(v[4] + b1.x); v[5] = sigmoidf_(v[5] + b1.y); v[6] = sigmoidf_(v[6] + b1.z); v[7] = sigmoidf_(v[7] + b1.w);
;                 store8((bf16_t*)(ws + WS_GATE) + (size_t)row * GT_COLS + cg_, v); }
	v_add_f32_e32 v49, 1.0, v49
	v_add_f32_e32 v42, 1.0, v42
	v_add_f32_e32 v43, 1.0, v43
	v_add_f32_e32 v44, 1.0, v44
	v_add_f32_e32 v45, 1.0, v45
	v_rcp_f32_e32 v46, v46
	v_rcp_f32_e32 v47, v47
	v_rcp_f32_e32 v48, v48
	v_rcp_f32_e32 v49, v49
	v_rcp_f32_e32 v42, v42
	v_rcp_f32_e32 v43, v43
	v_rcp_f32_e32 v44, v44
	v_rcp_f32_e32 v45, v45
	s_nop 0
	v_cvt_pk_bf16_f32 v228, v46, v47
	v_cvt_pk_bf16_f32 v229, v48, v49
	v_cvt_pk_bf16_f32 v230, v42, v43
	v_cvt_pk_bf16_f32 v231, v44, v45
	v_lshl_add_u64 v[236:237], v[148:149], 0, v[226:227]
	global_store_dwordx4 v[236:237], v[228:231], off
	v_pk_add_f32 v[38:39], v[38:39], v[218:219]
	v_pk_add_f32 v[40:41], v[40:41], v[220:221]
	v_pk_add_f32 v[34:35], v[34:35], v[222:223]
	v_pk_add_f32 v[36:37], v[36:37], v[224:225]
	v_mul_f32_e32 v38, 0xbfb8aa3b, v38
	v_mul_f32_e32 v39, 0xbfb8aa3b, v39
	v_mul_f32_e32 v40, 0xbfb8aa3b, v40
	v_mul_f32_e32 v41, 0xbfb8aa3b, v41
	v_mul_f32_e32 v34, 0xbfb8aa3b, v34
	v_mul_f32_e32 v35, 0xbfb8aa3b, v35
	v_mul_f32_e32 v36, 0xbfb8aa3b, v36
	v_mul_f32_e32 v37, 0xbfb8aa3b, v37
	v_exp_f32_e32 v38, v38
	v_exp_f32_e32 v39, v39
	v_exp_f32_e32 v40, v40
	v_exp_f32_e32 v41, v41
	v_exp_f32_e32 v34, v34
	v_exp_f32_e32 v35, v35
	v_exp_f32_e32 v36, v36
	v_exp_f32_e32 v37, v37
	v_add_f32_e32 v38, 1.0, v38
	v_add_f32_e32 v39, 1.0, v39
	v_add_f32_e32 v40, 1.0, v40
	v_add_f32_e32 v41, 1.0, v41
	v_add_f32_e32 v34, 1.0, v34
	v_add_f32_e32 v35, 1.0, v35
	v_add_f32_e32 v36, 1.0, v36
	v_add_f32_e32 v37, 1.0, v37
	v_rcp_f32_e32 v38, v38
	v_rcp_f32_e32 v39, v39
	v_rcp_f32_e32 v40, v40
	v_rcp_f32_e32 v41, v41
	v_rcp_f32_e32 v34, v34
	v_rcp_f32_e32 v35, v35
	v_rcp_f32_e32 v36, v36
	v_rcp_f32_e32 v37, v37
	s_nop 0
	v_cvt_pk_bf16_f32 v232, v38, v39
	v_cvt_pk_bf16_f32 v233, v40, v41
	v_cvt_pk_bf16_f32 v234, v34, v35
	v_cvt_pk_bf16_f32 v235, v36, v37
	v_lshl_add_u64 v[238:239], v[148:149], 0, v[226:227]
	global_store_dwordx4 v[238:239], v[232:235], off offset:256
	v_pk_add_f32 v[30:31], v[30:31], v[210:211]
	v_pk_add_f32 v[32:33], v[32:33], v[212:213]
	v_pk_add_f32 v[26:27], v[26:27], v[214:215]
	v_pk_add_f32 v[28:29], v[28:29], v[216:217]
	v_mul_f32_e32 v30, 0xbfb8aa3b, v30
	v_mul_f32_e32 v31, 0xbfb8aa3b, v31
	v_mul_f32_e32 v32, 0xbfb8aa3b, v32
	v_mul_f32_e32 v33, 0xbfb8aa3b, v33
	v_mul_f32_e32 v26, 0xbfb8aa3b, v26
	v_mul_f32_e32 v27, 0xbfb8aa3b, v27
	v_mul_f32_e32 v28, 0xbfb8aa3b, v28
	v_mul_f32_e32 v29, 0xbfb8aa3b, v29
	v_exp_f32_e32 v30, v30
	v_exp_f32_e32 v31, v31
	v_exp_f32_e32 v32, v32
	v_exp_f32_e32 v33, v33
	v_exp_f32_e32 v26, v26
	v_exp_f32_e32 v27, v27
	v_exp_f32_e32 v28, v28
	v_exp_f32_e32 v29, v29
	v_add_f32_e32 v30, 1.0, v30
	v_add_f32_e32 v31, 1.0, v31
	v_add_f32_e32 v32, 1.0, v32
	v_add_f32_e32 v33, 1.0, v33
	v_add_f32_e32 v26, 1.0, v26
	v_add_f32_e32 v27, 1.0, v27
	v_add_f32_e32 v28, 1.0, v28
	v_add_f32_e32 v29, 1.0, v29
	v_rcp_f32_e32 v30, v30
	v_rcp_f32_e32 v31, v31
	v_rcp_f32_e32 v32, v32
	v_rcp_f32_e32 v33, v33
	v_rcp_f32_e32 v26, v26
	v_rcp_f32_e32 v27, v27
	v_rcp_f32_e32 v28, v28
	v_rcp_f32_e32 v29, v29
	s_nop 0
	v_cvt_pk_bf16_f32 v228, v30, v31
	v_cvt_pk_bf16_f32 v229, v32, v33
	v_cvt_pk_bf16_f32 v230, v26, v27
	v_cvt_pk_bf16_f32 v231, v28, v29
	v_lshl_add_u64 v[236:237], v[150:151], 0, v[226:227]
	global_store_dwordx4 v[236:237], v[228:231], off
	v_pk_add_f32 v[22:23], v[22:23], v[218:219]
	v_pk_add_f32 v[24:25], v[24:25], v[220:221]
	v_pk_add_f32 v[18:19], v[18:19], v[222:223]
	v_pk_add_f32 v[20:21], v[20:21], v[224:225]
	v_mul_f32_e32 v22, 0xbfb8aa3b, v22
	v_mul_f32_e32 v23, 0xbfb8aa3b, v23
	v_mul_f32_e32 v24, 0xbfb8aa3b, v24
	v_mul_f32_e32 v25, 0xbfb8aa3b, v25
	v_mul_f32_e32 v18, 0xbfb8aa3b, v18
	v_mul_f32_e32 v19, 0xbfb8aa3b, v19
; __device__ __forceinline__ float sigmoidf_(float x) { return __builtin_amdgcn_rcpf(1.f + __expf(-x)); }
;     __device__ __forceinline__ void emit(int row, int pn, int col0, float* v) const {
;     ...
;             else { const int cg_ = col0 - 3840; const f32x4 b0 = ldg<f32x4>(f0 + cg_), b1 = ldg<f32x4>(f0 + cg_ + 4);
;                 v[0] = sigmoidf_(v[0] + b0.x); v[1] = sigmoidf_(v[1] + b0.y); v[2] = sigmoidf_(v[2] + b0.z); v[3] = sigmoidf_(v[3] + b0.w);
;                 v[4] = sigmoidf_(v[4] + b1.x); v[5] = sigmoidf_(v[5] + b1.y); v[6] = sigmoidf_(v[6] + b1.z); v[7] = sigmoidf_(v[7] + b1.w);
;                 store8((bf16_t*)(ws + WS_GATE) + (size_t)row * GT_COLS + cg_, v); }
	v_mul_f32_e32 v20, 0xbfb8aa3b, v20
	v_mul_f32_e32 v21, 0xbfb8aa3b, v21
	v_exp_f32_e32 v22, v22
	v_exp_f32_e32 v23, v23
	v_exp_f32_e32 v24, v24
	v_exp_f32_e32 v25, v25
	v_exp_f32_e32 v18, v18
	v_exp_f32_e32 v19, v19
	v_exp_f32_e32 v20, v20
	v_exp_f32_e32 v21, v21
	v_add_f32_e32 v22, 1.0, v22
	v_add_f32_e32 v23, 1.0, v23
	v_add_f32_e32 v24, 1.0, v24
	v_add_f32_e32 v25, 1.0, v25
	v_add_f32_e32 v18, 1.0, v18
	v_add_f32_e32 v19, 1.0, v19
	v_add_f32_e32 v20, 1.0, v20
	v_add_f32_e32 v21, 1.0, v21
	v_rcp_f32_e32 v22, v22
	v_rcp_f32_e32 v23, v23
	v_rcp_f32_e32 v24, v24
	v_rcp_f32_e32 v25, v25
	v_rcp_f32_e32 v18, v18
	v_rcp_f32_e32 v19, v19
	v_rcp_f32_e32 v20, v20
	v_rcp_f32_e32 v21, v21
	s_nop 0
	v_cvt_pk_bf16_f32 v232, v22, v23
	v_cvt_pk_bf16_f32 v233, v24, v25
	v_cvt_pk_bf16_f32 v234, v18, v19
	v_cvt_pk_bf16_f32 v235, v20, v21
	v_lshl_add_u64 v[238:239], v[150:151], 0, v[226:227]
	global_store_dwordx4 v[238:239], v[232:235], off offset:256
	v_pk_add_f32 v[14:15], v[14:15], v[210:211]
	v_pk_add_f32 v[16:17], v[16:17], v[212:213]
	v_pk_add_f32 v[10:11], v[10:11], v[214:215]
	v_pk_add_f32 v[12:13], v[12:13], v[216:217]
	v_mul_f32_e32 v14, 0xbfb8aa3b, v14
	v_mul_f32_e32 v15, 0xbfb8aa3b, v15
	v_mul_f32_e32 v16, 0xbfb8aa3b, v16
	v_mul_f32_e32 v17, 0xbfb8aa3b, v17
	v_mul_f32_e32 v10, 0xbfb8aa3b, v10
	v_mul_f32_e32 v11, 0xbfb8aa3b, v11
	v_mul_f32_e32 v12, 0xbfb8aa3b, v12
	v_mul_f32_e32 v13, 0xbfb8aa3b, v13
	v_exp_f32_e32 v14, v14
	v_exp_f32_e32 v15, v15
	v_exp_f32_e32 v16, v16
	v_exp_f32_e32 v17, v17
	v_exp_f32_e32 v10, v10
	v_exp_f32_e32 v11, v11
	v_exp_f32_e32 v12, v12
	v_exp_f32_e32 v13, v13
	v_add_f32_e32 v14, 1.0, v14
	v_add_f32_e32 v15, 1.0, v15
	v_add_f32_e32 v16, 1.0, v16
	v_add_f32_e32 v17, 1.0, v17
	v_add_f32_e32 v10, 1.0, v10
	v_add_f32_e32 v11, 1.0, v11
	v_add_f32_e32 v12, 1.0, v12
	v_add_f32_e32 v13, 1.0, v13
	v_rcp_f32_e32 v14, v14
	v_rcp_f32_e32 v15, v15
	v_rcp_f32_e32 v16, v16
	v_rcp_f32_e32 v17, v17
	v_rcp_f32_e32 v10, v10
	v_rcp_f32_e32 v11, v11
	v_rcp_f32_e32 v12, v12
	v_rcp_f32_e32 v13, v13
	s_nop 0
	v_cvt_pk_bf16_f32 v228, v14, v15
	v_cvt_pk_bf16_f32 v229, v16, v17
	v_cvt_pk_bf16_f32 v230, v10, v11
	v_cvt_pk_bf16_f32 v231, v12, v13
	v_lshl_add_u64 v[236:237], v[152:153], 0, v[226:227]
	global_store_dwordx4 v[236:237], v[228:231], off
	v_pk_add_f32 v[6:7], v[6:7], v[218:219]
	v_pk_add_f32 v[8:9], v[8:9], v[220:221]
	v_pk_add_f32 v[2:3], v[2:3], v[222:223]
	v_pk_add_f32 v[4:5], v[4:5], v[224:225]
	v_mul_f32_e32 v6, 0xbfb8aa3b, v6
	v_mul_f32_e32 v7, 0xbfb8aa3b, v7
	v_mul_f32_e32 v8, 0xbfb8aa3b, v8
	v_mul_f32_e32 v9, 0xbfb8aa3b, v9
	v_mul_f32_e32 v2, 0xbfb8aa3b, v2
	v_mul_f32_e32 v3, 0xbfb8aa3b, v3
	v_mul_f32_e32 v4, 0xbfb8aa3b, v4
	v_mul_f32_e32 v5, 0xbfb8aa3b, v5
	v_exp_f32_e32 v6, v6
	v_exp_f32_e32 v7, v7
	v_exp_f32_e32 v8, v8
	v_exp_f32_e32 v9, v9
	v_exp_f32_e32 v2, v2
	v_exp_f32_e32 v3, v3
	v_exp_f32_e32 v4, v4
	v_exp_f32_e32 v5, v5
	v_add_f32_e32 v6, 1.0, v6
	v_add_f32_e32 v7, 1.0, v7
	v_add_f32_e32 v8, 1.0, v8
	v_add_f32_e32 v9, 1.0, v9
	v_add_f32_e32 v2, 1.0, v2
	v_add_f32_e32 v3, 1.0, v3
	v_add_f32_e32 v4, 1.0, v4
	v_add_f32_e32 v5, 1.0, v5
	v_rcp_f32_e32 v6, v6
	v_rcp_f32_e32 v7, v7
	v_rcp_f32_e32 v8, v8
	v_rcp_f32_e32 v9, v9
	v_rcp_f32_e32 v2, v2
	v_rcp_f32_e32 v3, v3
	v_rcp_f32_e32 v4, v4
	v_rcp_f32_e32 v5, v5
	s_nop 0
	v_cvt_pk_bf16_f32 v232, v6, v7
	v_cvt_pk_bf16_f32 v233, v8, v9
	v_cvt_pk_bf16_f32 v234, v2, v3
	v_cvt_pk_bf16_f32 v235, v4, v5
	v_lshl_add_u64 v[238:239], v[152:153], 0, v[226:227]
	global_store_dwordx4 v[238:239], v[232:235], off offset:256
	s_mov_b32 s22, 1
	s_mov_b64 s[2:3], 0
	s_and_b64 vcc, exec, s[38:39]
	s_cbranch_vccz .LBB0_229
	s_branch .Lgt_tail

;     __device__ __forceinline__ const void* in(int i) const { return (const void*)uni64(t[i]); }
; #define PG8_STAGE(bufoff, gbase, voff) do { _Pragma("unroll") for (int _i = 0; _i < 2; ++_i) \
;         __builtin_amdgcn_global_load_lds((const unsigned*)((const char*)(gbase) + (voff)[_i]), (PG8_LAS unsigned*)(lds + (bufoff) + ldsw + _i * 8192), 16, 0, 0); } while (0)
; #define PG8_WAIT_V(n) asm volatile("s_waitcnt vmcnt(" #n ")" ::: "memory")
; #define PG8_BAR __builtin_amdgcn_s_barrier()
; template <class Epi, class Sched, bool ALIGN_EPI = false, bool SP2 = false>
; __device__ __forceinline__ void gemm_phase(PG8_LAS unsigned char* lds, const Gemm g, const Sched& S, const Epi& E) {
;     ...
;     if constexpr (SP2) {
;         PG8_STAGE(PG8_SB(0, 0), cB, voffB); PG8_STAGE(PG8_SB(0, 1), cB + hstepB, voffB); PG8_STAGE(PG8_SA(0, 0), cA, voffA); PG8_STAGE(PG8_SA(0, 1), cA + hstepA, voffA);
;         if (wr == 1) PG8_BAR;
;         PG8_WAIT_V(2); PG8_BAR;
;         PG8_STAGE(PG8_SB(1, 0), cB + kstep, voffB); PG8_STAGE(PG8_SA(1, 0), cA + kstep, voffA); PG8_STAGE(PG8_SB(1, 1), cB + hstepB + kstep, voffB);
;         PG8_WAIT_V(6); PG8_BAR;
; __device__ __forceinline__ void jobs_phase(LAS unsigned char* lds, const AP a, int l, int grp, int rep) {
;     ...
;             const int gq = j - NSCAN - NATT, pn = 15 + 2 * (gq / (TG / 256)), pm = gq % (TG / 256);
;             Epi E; E.kind = K_P; E.aux = 0; E.grp = grp; E.pad = 0; E.ws = a.ws(); E.f0 = (const float*)a.in(I_BGATE) + l * GT_COLS; E.f1 = nullptr; E.xi = nullptr; E.xo = nullptr;
;             run_gemm_unit(lds, (const bf16_t*)(a.ws() + WS_HB), 1024, (const bf16_t*)(a.ws() + WT_IN), TG, NP, 1024, E, pm, pn, 2);
.LBB0_225:
	s_andn2_b64 vcc, exec, s[0:1]
	s_cbranch_vccnz .LBB0_235
	s_branch .LBB0_226
.Lpd_entry:
	s_add_i32 s23, s23, 0x240
.LBB0_226:
	v_mov_b32_e32 v0, s73
	s_add_i32 s0, s23, 0xfffffd80
	s_waitcnt vmcnt(0)
	ds_read_b64 v[2:3], v0
	s_lshr_b32 s0, s0, 5
	s_and_b32 s44, s0, 0x7fffffe
	s_add_i32 s44, s44, -6
	v_readlane_b32 s0, v254, 37
	s_add_i32 s12, s44, 15
	s_waitcnt lgkmcnt(0)
	v_readfirstlane_b32 s3, v2
	v_mov_b32_e32 v0, s0
	ds_read_b64 v[4:5], v0
	v_mov_b32 v10, v192
	s_and_b32 s14, s23, 63
	v_lshrrev_b32_e32 v0, 5, v10
	v_and_b32_e32 v2, 4, v0
	v_lshrrev_b32_e32 v0, 1, v10
	v_readfirstlane_b32 s2, v3
	v_bfe_u32 v3, v10, 2, 2
	v_and_b32_e32 v0, 24, v0
	v_lshrrev_b32_e32 v13, 3, v10
	s_add_u32 s26, s3, 0x800000
	v_readfirstlane_b32 s27, v10
	v_or3_b32 v2, v2, v3, v0
	v_or_b32_e32 v3, 64, v13
	s_movk_i32 s0, 0x60
	s_addc_u32 s28, s2, 0
	s_lshr_b32 s19, s27, 6
	v_and_or_b32 v6, v3, s0, v2
	v_bfe_u32 v14, v10, 2, 4
	s_movk_i32 s0, 0x70
	s_lshr_b32 s17, s27, 8
	s_lshl_b32 s29, s19, 10
	v_lshlrev_b32_e32 v7, 4, v10
	v_and_b32_e32 v8, 32, v10
	v_and_or_b32 v3, v3, s0, v14
	s_lshl_b32 s15, s14, 19
	s_lshl_b32 s0, s12, 19
	v_bitop3_b32 v11, v7, v8, 48 bitop3:0x6c
	v_and_b32_e32 v12, 64, v10
	s_add_u32 s0, s26, s0
	v_or_b32_e32 v7, v11, v12
	v_and_or_b32 v2, v13, 32, v2
	s_addc_u32 s1, s28, 0
	s_add_i32 s30, s29, 0
	v_lshl_or_b32 v134, v2, 11, v7
	s_add_i32 m0, s30, 0x10000
	v_lshl_or_b32 v130, v6, 11, v7
	global_load_lds_dwordx4 v134, s[0:1]
	s_add_i32 m0, s30, 0x12000
	s_add_u32 s4, s0, 0x40000
	global_load_lds_dwordx4 v130, s[0:1]
	s_addc_u32 s5, s1, 0
	s_add_i32 m0, s30, 0x14000
	v_and_or_b32 v2, v13, 48, v14
	global_load_lds_dwordx4 v134, s[4:5]
	s_add_i32 m0, s30, 0x16000
	s_add_u32 s6, s3, s15
	s_addc_u32 s7, s2, 0
	global_load_lds_dwordx4 v130, s[4:5]
	s_add_u32 s4, s6, 0x2d00000
	s_addc_u32 s5, s7, 0
	s_add_i32 s31, s30, 0x2000
	v_lshl_or_b32 v136, v2, 11, v7
	s_mov_b32 m0, s30
	s_add_u32 s6, s6, 0x2d40000
	v_lshl_or_b32 v132, v3, 11, v7
	global_load_lds_dwordx4 v136, s[4:5]
	s_mov_b32 m0, s31
	s_addc_u32 s7, s7, 0
	s_add_i32 s40, s30, 0x4000
	global_load_lds_dwordx4 v132, s[4:5]
	s_mov_b32 m0, s40
	s_add_i32 s41, s30, 0x6000
	global_load_lds_dwordx4 v136, s[6:7]
	s_mov_b32 m0, s41
	v_mov_b32_e32 v135, v1
	global_load_lds_dwordx4 v132, s[6:7]
	v_mov_b32_e32 v131, v1
	v_mov_b32_e32 v137, v1
	v_mov_b32_e32 v133, v1
	s_waitcnt lgkmcnt(0)
	v_readfirstlane_b32 s7, v5
	v_readfirstlane_b32 s6, v4
	v_lshl_add_u64 v[8:9], s[0:1], 0, v[134:135]
	v_lshl_add_u64 v[6:7], s[0:1], 0, v[130:131]
	v_lshl_add_u64 v[4:5], s[4:5], 0, v[136:137]
	s_cmp_lg_u32 s17, 1
	v_lshl_add_u64 v[2:3], s[4:5], 0, v[132:133]
	s_cbranch_scc1 .LBB0_228
	s_barrier

; #define PG8_STAGE(bufoff, gbase, voff) do { _Pragma("unroll") for (int _i = 0; _i < 2; ++_i) \
;         __builtin_amdgcn_global_load_lds((const unsigned*)((const char*)(gbase) + (voff)[_i]), (PG8_LAS unsigned*)(lds + (bufoff) + ldsw + _i * 8192), 16, 0, 0); } while (0)
; #define PG8_LDA(dst, b, h) do { _Pragma("unroll") for (int m = 0; m < 4; ++m) _Pragma("unroll") for (int k = 0; k < 2; ++k) dst[m][k] = *(const PG8_LAS bf16x8*)(lds + PG8_SA(b, h) + aoff + m * 2048 + k * 1024); } while (0)
; #define PG8_LDB(dst, b, h) do { _Pragma("unroll") for (int n = 0; n < 2; ++n) _Pragma("unroll") for (int k = 0; k < 2; ++k) dst[n][k] = *(const PG8_LAS bf16x8*)(lds + PG8_SB(b, h) + boff + n * 2048 + k * 1024); } while (0)
; #define PG8_MMA(ai, bj, At, Bt) do { __builtin_amdgcn_s_setprio(1); _Pragma("unroll") for (int m = 0; m < 4; ++m) _Pragma("unroll") for (int n = 0; n < 2; ++n) _Pragma("unroll") for (int k = 0; k < 2; ++k) \
;         acc[ai][bj][m][n] = __builtin_amdgcn_mfma_f32_16x16x32_bf16(Bt[n][k], At[m][k], acc[ai][bj][m][n], 0, 0, 0); __builtin_amdgcn_s_setprio(0); } while (0)
; #define PG8_WAIT_V(n) asm volatile("s_waitcnt vmcnt(" #n ")" ::: "memory")
; #define PG8_WAIT_L(n) asm volatile("s_waitcnt lgkmcnt(" #n ")" ::: "memory")
; #define PG8_BAR __builtin_amdgcn_s_barrier()
; #define PG8_SCHED __builtin_amdgcn_sched_barrier(0)
; template <class Epi, class Sched, bool ALIGN_EPI = false, bool SP2 = false>
; __device__ __forceinline__ void gemm_phase(PG8_LAS unsigned char* lds, const Gemm g, const Sched& S, const Epi& E) {
;     ...
;             PG8_LDB(B0, 0, 0); PG8_LDB(B1, 0, 1); PG8_SCHED; PG8_LDA(At, 0, 0); PG8_STAGE(PG8_SA(1, 1), a1 + hstepA, voffA);
;             PG8_WAIT_V(8); PG8_WAIT_L(0); PG8_BAR; PG8_MMA(0, 0, At, B0); PG8_MMA(0, 1, At, B1); PG8_BAR; PG8_SCHED;
;             PG8_LDA(At, 0, 1); PG8_STAGE(PG8_SB(0, 0), b2, voffB); PG8_STAGE(PG8_SB(0, 1), b2 + hstepB, voffB); PG8_STAGE(PG8_SA(0, 0), a2, voffA);
;             PG8_WAIT_V(8); PG8_WAIT_L(0); PG8_BAR; PG8_MMA(1, 0, At, B0); PG8_MMA(1, 1, At, B1); PG8_BAR; PG8_SCHED;
.LBB0_230:
	s_add_u32 s20, s45, s2
	s_addc_u32 s21, s46, s3
	s_add_u32 s20, s20, 0x2d00100
	s_addc_u32 s21, s21, 0
	s_add_u32 s49, s17, s2
	s_addc_u32 s50, s19, s3
	s_add_i32 s51, 0, 0x10000
	s_cmpk_eq_i32 s2, 0x700
	s_cselect_b32 s25, s5, s21
	s_cselect_b32 s24, s4, s20
	v_add_u32_e32 v0, s51, v160
	s_cselect_b32 s21, s14, s50
	s_cselect_b32 s20, s15, s49
	s_add_i32 s49, 0, 0x14000
	ds_read_b128 v[164:167], v0
	ds_read_b128 v[168:171], v0 offset:1024
	ds_read_b128 v[172:175], v0 offset:2048
	ds_read_b128 v[180:183], v0 offset:3072
	v_add_u32_e32 v0, s49, v160
	ds_read_b128 v[184:187], v0
	ds_read_b128 v[188:191], v0 offset:1024
	ds_read_b128 v[210:213], v0 offset:2048
	ds_read_b128 v[214:217], v0 offset:3072
	v_lshl_add_u64 v[158:159], v[156:157], 0, s[2:3]
	s_add_i32 m0, s30, 0xc000
	ds_read_b128 v[218:221], v162
	ds_read_b128 v[222:225], v162 offset:1024
	ds_read_b128 v[226:229], v162 offset:2048
	ds_read_b128 v[230:233], v162 offset:3072
	ds_read_b128 v[234:237], v162 offset:4096
	ds_read_b128 v[238:241], v162 offset:5120
	ds_read_b128 v[242:245], v162 offset:6144
	ds_read_b128 v[246:249], v162 offset:7168
	global_load_lds_dwordx4 v[158:159], off
	v_lshl_add_u64 v[158:159], v[154:155], 0, s[2:3]
	s_add_i32 m0, s30, 0xe000
	s_nop 0
	global_load_lds_dwordx4 v[158:159], off
	s_waitcnt vmcnt(8)
	s_waitcnt lgkmcnt(0)
	s_barrier
	s_setprio 1
	s_waitcnt lgkmcnt(0)
	v_mfma_f32_16x16x32_bf16 v[126:129], v[164:167], v[218:221], v[126:129]
	v_mfma_f32_16x16x32_bf16 v[122:125], v[172:175], v[218:221], v[122:125]
	v_mfma_f32_16x16x32_bf16 v[110:113], v[164:167], v[226:229], v[110:113]
	v_mfma_f32_16x16x32_bf16 v[106:109], v[172:175], v[226:229], v[106:109]
	v_mfma_f32_16x16x32_bf16 v[94:97], v[164:167], v[234:237], v[94:97]
	v_mfma_f32_16x16x32_bf16 v[90:93], v[172:175], v[234:237], v[90:93]
	v_mfma_f32_16x16x32_bf16 v[78:81], v[164:167], v[242:245], v[78:81]
	v_mfma_f32_16x16x32_bf16 v[74:77], v[172:175], v[242:245], v[74:77]
	v_mfma_f32_16x16x32_bf16 v[126:129], v[168:171], v[222:225], v[126:129]
	v_mfma_f32_16x16x32_bf16 v[122:125], v[180:183], v[222:225], v[122:125]
	v_mfma_f32_16x16x32_bf16 v[110:113], v[168:171], v[230:233], v[110:113]
	v_mfma_f32_16x16x32_bf16 v[106:109], v[180:183], v[230:233], v[106:109]
	v_mfma_f32_16x16x32_bf16 v[94:97], v[168:171], v[238:241], v[94:97]
	v_mfma_f32_16x16x32_bf16 v[90:93], v[180:183], v[238:241], v[90:93]
	v_mfma_f32_16x16x32_bf16 v[78:81], v[168:171], v[246:249], v[78:81]
	v_mfma_f32_16x16x32_bf16 v[74:77], v[180:183], v[246:249], v[74:77]
	s_setprio 0
	s_setprio 1
	v_mfma_f32_16x16x32_bf16 v[118:121], v[184:187], v[218:221], v[118:121]
	v_mfma_f32_16x16x32_bf16 v[114:117], v[210:213], v[218:221], v[114:117]
	v_mfma_f32_16x16x32_bf16 v[102:105], v[184:187], v[226:229], v[102:105]
	v_mfma_f32_16x16x32_bf16 v[98:101], v[210:213], v[226:229], v[98:101]
	v_mfma_f32_16x16x32_bf16 v[86:89], v[184:187], v[234:237], v[86:89]
	v_mfma_f32_16x16x32_bf16 v[82:85], v[210:213], v[234:237], v[82:85]
	v_mfma_f32_16x16x32_bf16 v[70:73], v[184:187], v[242:245], v[70:73]
	v_mfma_f32_16x16x32_bf16 v[66:69], v[210:213], v[242:245], v[66:69]
	v_mfma_f32_16x16x32_bf16 v[118:121], v[188:191], v[222:225], v[118:121]
	v_mfma_f32_16x16x32_bf16 v[114:117], v[214:217], v[222:225], v[114:117]
	v_mfma_f32_16x16x32_bf16 v[102:105], v[188:191], v[230:233], v[102:105]
	v_mfma_f32_16x16x32_bf16 v[98:101], v[214:217], v[230:233], v[98:101]
	v_mfma_f32_16x16x32_bf16 v[86:89], v[188:191], v[238:241], v[86:89]
	v_mfma_f32_16x16x32_bf16 v[82:85], v[214:217], v[238:241], v[82:85]
	v_mfma_f32_16x16x32_bf16 v[70:73], v[188:191], v[246:249], v[70:73]
	v_mfma_f32_16x16x32_bf16 v[66:69], v[214:217], v[246:249], v[66:69]
	s_setprio 0
	s_barrier
	s_add_i32 s50, s51, s29
	v_lshl_add_u64 v[158:159], s[20:21], 0, v[134:135]
	s_mov_b32 m0, s50
	ds_read_b128 v[218:221], v162 offset:16384
	ds_read_b128 v[222:225], v162 offset:17408
	ds_read_b128 v[226:229], v162 offset:18432
	ds_read_b128 v[230:233], v162 offset:19456
	ds_read_b128 v[234:237], v162 offset:20480
	ds_read_b128 v[238:241], v162 offset:21504
	ds_read_b128 v[242:245], v162 offset:22528
	ds_read_b128 v[246:249], v162 offset:23552
	global_load_lds_dwordx4 v[158:159], off
	s_add_i32 m0, s50, 0x2000
	s_add_u32 s50, s20, 0x40000
	v_lshl_add_u64 v[176:177], s[20:21], 0, v[130:131]
	s_addc_u32 s51, s21, 0
	s_add_i32 s49, s49, s29
	global_load_lds_dwordx4 v[176:177], off
	v_lshl_add_u64 v[250:251], s[50:51], 0, v[134:135]
	s_mov_b32 m0, s49
	v_lshl_add_u64 v[200:201], s[24:25], 0, v[132:133]
	global_load_lds_dwordx4 v[250:251], off
	v_lshl_add_u64 v[250:251], s[50:51], 0, v[130:131]
	s_add_i32 m0, s49, 0x2000
	s_nop 0
	global_load_lds_dwordx4 v[250:251], off
	v_lshl_add_u64 v[250:251], s[24:25], 0, v[136:137]
	s_mov_b32 m0, s30
	s_nop 0
	global_load_lds_dwordx4 v[250:251], off
	s_mov_b32 m0, s31
	s_nop 0
	global_load_lds_dwordx4 v[200:201], off
	s_waitcnt vmcnt(8)
	s_waitcnt lgkmcnt(0)
	s_barrier
; #define PG8_STAGE(bufoff, gbase, voff) do { _Pragma("unroll") for (int _i = 0; _i < 2; ++_i) \
;         __builtin_amdgcn_global_load_lds((const unsigned*)((const char*)(gbase) + (voff)[_i]), (PG8_LAS unsigned*)(lds + (bufoff) + ldsw + _i * 8192), 16, 0, 0); } while (0)
; #define PG8_LDA(dst, b, h) do { _Pragma("unroll") for (int m = 0; m < 4; ++m) _Pragma("unroll") for (int k = 0; k < 2; ++k) dst[m][k] = *(const PG8_LAS bf16x8*)(lds + PG8_SA(b, h) + aoff + m * 2048 + k * 1024); } while (0)
; #define PG8_LDB(dst, b, h) do { _Pragma("unroll") for (int n = 0; n < 2; ++n) _Pragma("unroll") for (int k = 0; k < 2; ++k) dst[n][k] = *(const PG8_LAS bf16x8*)(lds + PG8_SB(b, h) + boff + n * 2048 + k * 1024); } while (0)
; #define PG8_MMA(ai, bj, At, Bt) do { __builtin_amdgcn_s_setprio(1); _Pragma("unroll") for (int m = 0; m < 4; ++m) _Pragma("unroll") for (int n = 0; n < 2; ++n) _Pragma("unroll") for (int k = 0; k < 2; ++k) \
;         acc[ai][bj][m][n] = __builtin_amdgcn_mfma_f32_16x16x32_bf16(Bt[n][k], At[m][k], acc[ai][bj][m][n], 0, 0, 0); __builtin_amdgcn_s_setprio(0); } while (0)
; #define PG8_WAIT_V(n) asm volatile("s_waitcnt vmcnt(" #n ")" ::: "memory")
; #define PG8_WAIT_L(n) asm volatile("s_waitcnt lgkmcnt(" #n ")" ::: "memory")
; #define PG8_BAR __builtin_amdgcn_s_barrier()
; #define PG8_SCHED __builtin_amdgcn_sched_barrier(0)
; template <class Epi, class Sched, bool ALIGN_EPI = false, bool SP2 = false>
; __device__ __forceinline__ void gemm_phase(PG8_LAS unsigned char* lds, const Gemm g, const Sched& S, const Epi& E) {
;     ...
;             PG8_WAIT_V(8); PG8_WAIT_L(0); PG8_BAR; PG8_MMA(1, 0, At, B0); PG8_MMA(1, 1, At, B1); PG8_BAR; PG8_SCHED;
;             PG8_LDB(B0, 1, 0); PG8_LDB(B1, 1, 1); PG8_SCHED; PG8_LDA(At, 1, 0); PG8_STAGE(PG8_SA(0, 1), a2 + hstepA, voffA);
;             PG8_WAIT_V(8); PG8_WAIT_L(0); PG8_BAR; PG8_MMA(0, 0, At, B0); PG8_MMA(0, 1, At, B1); PG8_BAR; PG8_SCHED;
	s_setprio 1
	s_waitcnt lgkmcnt(0)
	v_mfma_f32_16x16x32_bf16 v[62:65], v[164:167], v[218:221], v[62:65]
	v_mfma_f32_16x16x32_bf16 v[58:61], v[172:175], v[218:221], v[58:61]
	v_mfma_f32_16x16x32_bf16 v[46:49], v[164:167], v[226:229], v[46:49]
	v_mfma_f32_16x16x32_bf16 v[42:45], v[172:175], v[226:229], v[42:45]
	v_mfma_f32_16x16x32_bf16 v[30:33], v[164:167], v[234:237], v[30:33]
	v_mfma_f32_16x16x32_bf16 v[26:29], v[172:175], v[234:237], v[26:29]
	v_mfma_f32_16x16x32_bf16 v[14:17], v[164:167], v[242:245], v[14:17]
	v_mfma_f32_16x16x32_bf16 v[10:13], v[172:175], v[242:245], v[10:13]
	v_mfma_f32_16x16x32_bf16 v[62:65], v[168:171], v[222:225], v[62:65]
	v_mfma_f32_16x16x32_bf16 v[58:61], v[180:183], v[222:225], v[58:61]
	v_mfma_f32_16x16x32_bf16 v[46:49], v[168:171], v[230:233], v[46:49]
	v_mfma_f32_16x16x32_bf16 v[42:45], v[180:183], v[230:233], v[42:45]
	v_mfma_f32_16x16x32_bf16 v[30:33], v[168:171], v[238:241], v[30:33]
	v_mfma_f32_16x16x32_bf16 v[26:29], v[180:183], v[238:241], v[26:29]
	v_mfma_f32_16x16x32_bf16 v[14:17], v[168:171], v[246:249], v[14:17]
	v_mfma_f32_16x16x32_bf16 v[10:13], v[180:183], v[246:249], v[10:13]
	s_setprio 0
	s_setprio 1
	v_mfma_f32_16x16x32_bf16 v[54:57], v[184:187], v[218:221], v[54:57]
	v_mfma_f32_16x16x32_bf16 v[50:53], v[210:213], v[218:221], v[50:53]
	v_mfma_f32_16x16x32_bf16 v[38:41], v[184:187], v[226:229], v[38:41]
	v_mfma_f32_16x16x32_bf16 v[34:37], v[210:213], v[226:229], v[34:37]
	v_mfma_f32_16x16x32_bf16 v[22:25], v[184:187], v[234:237], v[22:25]
	v_mfma_f32_16x16x32_bf16 v[18:21], v[210:213], v[234:237], v[18:21]
	v_mfma_f32_16x16x32_bf16 v[6:9], v[184:187], v[242:245], v[6:9]
	v_mfma_f32_16x16x32_bf16 v[2:5], v[210:213], v[242:245], v[2:5]
	v_mfma_f32_16x16x32_bf16 v[54:57], v[188:191], v[222:225], v[54:57]
	v_mfma_f32_16x16x32_bf16 v[50:53], v[214:217], v[222:225], v[50:53]
	v_mfma_f32_16x16x32_bf16 v[38:41], v[188:191], v[230:233], v[38:41]
	v_mfma_f32_16x16x32_bf16 v[34:37], v[214:217], v[230:233], v[34:37]
	v_mfma_f32_16x16x32_bf16 v[22:25], v[188:191], v[238:241], v[22:25]
	v_mfma_f32_16x16x32_bf16 v[18:21], v[214:217], v[238:241], v[18:21]
	v_mfma_f32_16x16x32_bf16 v[6:9], v[188:191], v[246:249], v[6:9]
	v_mfma_f32_16x16x32_bf16 v[2:5], v[214:217], v[246:249], v[2:5]
	s_setprio 0
	s_barrier
	s_add_i32 s49, 0, 0x18000
	v_add_u32_e32 v0, s49, v160
	s_add_i32 s50, 0, 0x1c000
	ds_read_b128 v[164:167], v0
	ds_read_b128 v[168:171], v0 offset:1024
	ds_read_b128 v[172:175], v0 offset:2048
	ds_read_b128 v[180:183], v0 offset:3072
	v_add_u32_e32 v0, s50, v160
	ds_read_b128 v[184:187], v0
	ds_read_b128 v[188:191], v0 offset:1024
	ds_read_b128 v[210:213], v0 offset:2048
	ds_read_b128 v[214:217], v0 offset:3072
	s_add_u32 s24, s24, 0x40000
	s_addc_u32 s25, s25, 0
	s_mov_b32 m0, s40
	v_lshl_add_u64 v[202:203], s[24:25], 0, v[136:137]
	ds_read_b128 v[218:221], v162 offset:32768
	ds_read_b128 v[222:225], v162 offset:33792
	ds_read_b128 v[226:229], v162 offset:34816
	ds_read_b128 v[230:233], v162 offset:35840
	ds_read_b128 v[234:237], v162 offset:36864
	ds_read_b128 v[238:241], v162 offset:37888
	ds_read_b128 v[242:245], v162 offset:38912
	ds_read_b128 v[246:249], v162 offset:39936
	global_load_lds_dwordx4 v[202:203], off
	v_lshl_add_u64 v[202:203], s[24:25], 0, v[132:133]
	s_mov_b32 m0, s41
	s_nop 0
	global_load_lds_dwordx4 v[202:203], off
	s_waitcnt vmcnt(8)
	s_waitcnt lgkmcnt(0)
	s_barrier
	s_setprio 1
	s_waitcnt lgkmcnt(0)
	v_mfma_f32_16x16x32_bf16 v[126:129], v[164:167], v[218:221], v[126:129]
	v_mfma_f32_16x16x32_bf16 v[122:125], v[172:175], v[218:221], v[122:125]
	v_mfma_f32_16x16x32_bf16 v[110:113], v[164:167], v[226:229], v[110:113]
	v_mfma_f32_16x16x32_bf16 v[106:109], v[172:175], v[226:229], v[106:109]
	v_mfma_f32_16x16x32_bf16 v[94:97], v[164:167], v[234:237], v[94:97]
	v_mfma_f32_16x16x32_bf16 v[90:93], v[172:175], v[234:237], v[90:93]
	v_mfma_f32_16x16x32_bf16 v[78:81], v[164:167], v[242:245], v[78:81]
	v_mfma_f32_16x16x32_bf16 v[74:77], v[172:175], v[242:245], v[74:77]
	v_mfma_f32_16x16x32_bf16 v[126:129], v[168:171], v[222:225], v[126:129]
	v_mfma_f32_16x16x32_bf16 v[122:125], v[180:183], v[222:225], v[122:125]
	v_mfma_f32_16x16x32_bf16 v[110:113], v[168:171], v[230:233], v[110:113]
	v_mfma_f32_16x16x32_bf16 v[106:109], v[180:183], v[230:233], v[106:109]
	v_mfma_f32_16x16x32_bf16 v[94:97], v[168:171], v[238:241], v[94:97]
	v_mfma_f32_16x16x32_bf16 v[90:93], v[180:183], v[238:241], v[90:93]
	v_mfma_f32_16x16x32_bf16 v[78:81], v[168:171], v[246:249], v[78:81]
	v_mfma_f32_16x16x32_bf16 v[74:77], v[180:183], v[246:249], v[74:77]
	s_setprio 0
	s_setprio 1
	v_mfma_f32_16x16x32_bf16 v[118:121], v[184:187], v[218:221], v[118:121]
	v_mfma_f32_16x16x32_bf16 v[114:117], v[210:213], v[218:221], v[114:117]
	v_mfma_f32_16x16x32_bf16 v[102:105], v[184:187], v[226:229], v[102:105]
	v_mfma_f32_16x16x32_bf16 v[98:101], v[210:213], v[226:229], v[98:101]
	v_mfma_f32_16x16x32_bf16 v[86:89], v[184:187], v[234:237], v[86:89]
	v_mfma_f32_16x16x32_bf16 v[82:85], v[210:213], v[234:237], v[82:85]
	v_mfma_f32_16x16x32_bf16 v[70:73], v[184:187], v[242:245], v[70:73]
	v_mfma_f32_16x16x32_bf16 v[66:69], v[210:213], v[242:245], v[66:69]
	v_mfma_f32_16x16x32_bf16 v[118:121], v[188:191], v[222:225], v[118:121]
	v_mfma_f32_16x16x32_bf16 v[114:117], v[214:217], v[222:225], v[114:117]
	v_mfma_f32_16x16x32_bf16 v[102:105], v[188:191], v[230:233], v[102:105]
	v_mfma_f32_16x16x32_bf16 v[98:101], v[214:217], v[230:233], v[98:101]
	v_mfma_f32_16x16x32_bf16 v[86:89], v[188:191], v[238:241], v[86:89]
	v_mfma_f32_16x16x32_bf16 v[82:85], v[214:217], v[238:241], v[82:85]
	v_mfma_f32_16x16x32_bf16 v[70:73], v[188:191], v[246:249], v[70:73]
	v_mfma_f32_16x16x32_bf16 v[66:69], v[214:217], v[246:249], v[66:69]
	s_setprio 0
	s_barrier
; #define PG8_STAGE(bufoff, gbase, voff) do { _Pragma("unroll") for (int _i = 0; _i < 2; ++_i) \
;         __builtin_amdgcn_global_load_lds((const unsigned*)((const char*)(gbase) + (voff)[_i]), (PG8_LAS unsigned*)(lds + (bufoff) + ldsw + _i * 8192), 16, 0, 0); } while (0)
; #define PG8_LDA(dst, b, h) do { _Pragma("unroll") for (int m = 0; m < 4; ++m) _Pragma("unroll") for (int k = 0; k < 2; ++k) dst[m][k] = *(const PG8_LAS bf16x8*)(lds + PG8_SA(b, h) + aoff + m * 2048 + k * 1024); } while (0)
; #define PG8_MMA(ai, bj, At, Bt) do { __builtin_amdgcn_s_setprio(1); _Pragma("unroll") for (int m = 0; m < 4; ++m) _Pragma("unroll") for (int n = 0; n < 2; ++n) _Pragma("unroll") for (int k = 0; k < 2; ++k) \
;         acc[ai][bj][m][n] = __builtin_amdgcn_mfma_f32_16x16x32_bf16(Bt[n][k], At[m][k], acc[ai][bj][m][n], 0, 0, 0); __builtin_amdgcn_s_setprio(0); } while (0)
; #define PG8_WAIT_V(n) asm volatile("s_waitcnt vmcnt(" #n ")" ::: "memory")
; #define PG8_WAIT_L(n) asm volatile("s_waitcnt lgkmcnt(" #n ")" ::: "memory")
; #define PG8_BAR __builtin_amdgcn_s_barrier()
; #define PG8_SCHED __builtin_amdgcn_sched_barrier(0)
; template <class Epi, class Sched, bool ALIGN_EPI = false, bool SP2 = false>
; __device__ __forceinline__ void gemm_phase(PG8_LAS unsigned char* lds, const Gemm g, const Sched& S, const Epi& E) {
;     ...
;             PG8_LDA(At, 1, 1); PG8_STAGE(PG8_SB(1, 0), b3, voffB); PG8_STAGE(PG8_SB(1, 1), b3 + hstepB, voffB); PG8_STAGE(PG8_SA(1, 0), a3, voffA);
;             PG8_WAIT_V(8); PG8_WAIT_L(0); PG8_BAR; PG8_MMA(1, 0, At, B0); PG8_MMA(1, 1, At, B1); PG8_BAR; PG8_SCHED;
;     ...
;     PG8_WAIT_V(0);
;     if constexpr (!ALIGN_EPI) { if (wr == 0) PG8_BAR; }
;     PG8_BAR;
	s_add_i32 s24, s49, s29
	v_lshl_add_u64 v[158:159], v[158:159], 0, s[34:35]
	s_mov_b32 m0, s24
	ds_read_b128 v[218:221], v162 offset:49152
	ds_read_b128 v[222:225], v162 offset:50176
	ds_read_b128 v[226:229], v162 offset:51200
	ds_read_b128 v[230:233], v162 offset:52224
	ds_read_b128 v[234:237], v162 offset:53248
	ds_read_b128 v[238:241], v162 offset:54272
	ds_read_b128 v[242:245], v162 offset:55296
	ds_read_b128 v[246:249], v162 offset:56320
	global_load_lds_dwordx4 v[158:159], off
	s_add_i32 m0, s24, 0x2000
	s_add_u32 s20, s20, 0x40080
	v_lshl_add_u64 v[158:159], v[176:177], 0, s[34:35]
	s_addc_u32 s21, s21, 0
	s_add_i32 s24, s50, s29
	global_load_lds_dwordx4 v[158:159], off
	v_lshl_add_u64 v[158:159], s[20:21], 0, v[134:135]
	s_mov_b32 m0, s24
	s_nop 0
	global_load_lds_dwordx4 v[158:159], off
	v_lshl_add_u64 v[158:159], s[20:21], 0, v[130:131]
	s_add_i32 m0, s24, 0x2000
	s_nop 0
	global_load_lds_dwordx4 v[158:159], off
	v_lshl_add_u64 v[158:159], v[250:251], 0, s[34:35]
	s_mov_b32 m0, s42
	s_nop 0
	global_load_lds_dwordx4 v[158:159], off
	v_lshl_add_u64 v[158:159], v[200:201], 0, s[34:35]
	s_mov_b32 m0, s43
	s_nop 0
	global_load_lds_dwordx4 v[158:159], off
	s_waitcnt vmcnt(8)
	s_waitcnt lgkmcnt(0)
	s_barrier
	s_setprio 1
	s_waitcnt lgkmcnt(0)
	v_mfma_f32_16x16x32_bf16 v[62:65], v[164:167], v[218:221], v[62:65]
	v_mfma_f32_16x16x32_bf16 v[58:61], v[172:175], v[218:221], v[58:61]
	v_mfma_f32_16x16x32_bf16 v[46:49], v[164:167], v[226:229], v[46:49]
	v_mfma_f32_16x16x32_bf16 v[42:45], v[172:175], v[226:229], v[42:45]
	v_mfma_f32_16x16x32_bf16 v[30:33], v[164:167], v[234:237], v[30:33]
	v_mfma_f32_16x16x32_bf16 v[26:29], v[172:175], v[234:237], v[26:29]
	v_mfma_f32_16x16x32_bf16 v[14:17], v[164:167], v[242:245], v[14:17]
	v_mfma_f32_16x16x32_bf16 v[10:13], v[172:175], v[242:245], v[10:13]
	v_mfma_f32_16x16x32_bf16 v[62:65], v[168:171], v[222:225], v[62:65]
	v_mfma_f32_16x16x32_bf16 v[58:61], v[180:183], v[222:225], v[58:61]
	v_mfma_f32_16x16x32_bf16 v[46:49], v[168:171], v[230:233], v[46:49]
	v_mfma_f32_16x16x32_bf16 v[42:45], v[180:183], v[230:233], v[42:45]
	v_mfma_f32_16x16x32_bf16 v[30:33], v[168:171], v[238:241], v[30:33]
	v_mfma_f32_16x16x32_bf16 v[26:29], v[180:183], v[238:241], v[26:29]
	v_mfma_f32_16x16x32_bf16 v[14:17], v[168:171], v[246:249], v[14:17]
	v_mfma_f32_16x16x32_bf16 v[10:13], v[180:183], v[246:249], v[10:13]
	s_setprio 0
	s_setprio 1
	v_mfma_f32_16x16x32_bf16 v[54:57], v[184:187], v[218:221], v[54:57]
	v_mfma_f32_16x16x32_bf16 v[50:53], v[210:213], v[218:221], v[50:53]
	v_mfma_f32_16x16x32_bf16 v[38:41], v[184:187], v[226:229], v[38:41]
	v_mfma_f32_16x16x32_bf16 v[34:37], v[210:213], v[226:229], v[34:37]
	v_mfma_f32_16x16x32_bf16 v[22:25], v[184:187], v[234:237], v[22:25]
	v_mfma_f32_16x16x32_bf16 v[18:21], v[210:213], v[234:237], v[18:21]
	v_mfma_f32_16x16x32_bf16 v[6:9], v[184:187], v[242:245], v[6:9]
	v_mfma_f32_16x16x32_bf16 v[2:5], v[210:213], v[242:245], v[2:5]
	v_mfma_f32_16x16x32_bf16 v[54:57], v[188:191], v[222:225], v[54:57]
	v_mfma_f32_16x16x32_bf16 v[50:53], v[214:217], v[222:225], v[50:53]
	v_mfma_f32_16x16x32_bf16 v[38:41], v[188:191], v[230:233], v[38:41]
	v_mfma_f32_16x16x32_bf16 v[34:37], v[214:217], v[230:233], v[34:37]
	v_mfma_f32_16x16x32_bf16 v[22:25], v[188:191], v[238:241], v[22:25]
	v_mfma_f32_16x16x32_bf16 v[18:21], v[214:217], v[238:241], v[18:21]
	v_mfma_f32_16x16x32_bf16 v[6:9], v[188:191], v[246:249], v[6:9]
	v_mfma_f32_16x16x32_bf16 v[2:5], v[214:217], v[246:249], v[2:5]
	s_setprio 0
	s_barrier
	s_add_i32 s48, s48, 2
	s_add_u32 s2, s2, 0x100
	s_addc_u32 s3, s3, 0
	s_cmp_gt_u32 s48, 13
	s_cbranch_scc0 .LBB0_230
	s_add_i32 s2, s22, s12
	s_cmp_lt_i32 s2, 15
	s_cbranch_scc1 .Lpd_epi
	s_add_i32 s2, s22, s12
	s_branch .Lgt_epi
.Lgt_tail:
.Lpd_tail:
	s_waitcnt vmcnt(0)
	s_cmpk_gt_u32 s27, 0xff
	s_cbranch_scc1 .LBB0_234
	s_barrier
.LBB0_234:
	s_barrier
	s_waitcnt lgkmcnt(0)
	s_barrier
	s_cmp_gt_i32 s12, 14
	s_cbranch_scc1 .LBB0_235
	s_cmp_gt_u32 s27, 63
	s_cbranch_scc1 .LBB0_235
	buffer_wbl2 sc1
	s_waitcnt vmcnt(0)
	v_mov_b64_e32 v[2:3], s[96:97]
	s_mov_b64 exec, 1
	flat_atomic_add v[2:3], v194 offset:32
	s_mov_b64 exec, -1
	s_waitcnt vmcnt(0) lgkmcnt(0)

;     __device__ __forceinline__ const void* in(int i) const { return (const void*)uni64(t[i]); }
;     __device__ __forceinline__ float* out() const { return (float*)uni64(t[33]); }
; __global__ void __launch_bounds__(NTHREADS, 2) mega(Args a_unused) {
;     ...
;             case 1: E.kind = K_P; boff = WT_IN; N = 3840; break;
;             case 3:
;                 if (gi == 0) { E.kind = K_Q; aoff = WS_CQN; lda = 256; boff = WT_UQ; N = 768; K = 256; }
;                 else if (gi == 1) { E.kind = K_KV; aoff = WS_CKVN; lda = 128; boff = WT_UKV; N = 1024; K = 128; }
;                 else { E.kind = K_LORA; E.f0 = (const float*)a.in(I_W0) + l * 512; E.f1 = (const float*)a.in(I_A0) + l * 512; aoff = WS_LIN; lda = 256; boff = WT_LORA; N = 1536; K = 256; }
;                 break;
;             case 6: E.kind = K_BR3; aoff = WS_ORW; lda = 512; boff = WT_BR; N = 1024; K = 512; nbr = 3; brA = 16 * MiB; brB = (size_t)1024 * 512 * 2; break;
;             case 7: E.kind = K_WO; E.xi = xin; E.xo = a.out(); boff = WT_O; N = 1024; break;
;             case 9: break;
;             default: E.kind = K_DN; E.xi = a.out(); E.xo = a.out(); aoff = WS_ACT; lda = DFF; boff = WT_DN; N = 1024; K = DFF; break;
;             }
;             run_gemm(lds, (const bf16_t*)(ws + aoff), lda, (const bf16_t*)(ws + boff), TG, N, K, E, nbr, brA, brB);
.LBB0_442:
	s_andn2_b64 vcc, exec, s[24:25]
	s_cbranch_vccnz .LBB0_444
	s_mov_b64 s[16:17], 0
	v_writelane_b32 v255, s16, 19
	s_mov_b32 s29, 1
	s_movk_i32 s15, 0x400
	s_mov_b32 s14, 9
	s_mov_b64 s[68:69], 0
	s_mov_b64 s[2:3], 0x800000
	s_mov_b64 s[18:19], 0x2d00000
	s_mov_b32 s28, 0
	v_writelane_b32 v255, s17, 20
	s_mov_b64 s[74:75], 0
	s_mov_b64 s[66:67], 0
	s_mov_b64 s[16:17], 0
	s_mov_b64 s[72:73], 0
	s_mov_b64 s[64:65], 0
